# opt24 static priority: leading half (wr=0) at s_setprio 1 during its epilogue so its next load segment runs under the trailing half's epilogue; reset at unit head and phase boundaries; on v063
# baseline (speedup 1.0000x reference)
.LBB0_10:
	s_or_b64 exec, exec, s[4:5]
	s_load_dwordx16 s[16:31], s[0:1], 0x0
	s_load_dwordx16 s[36:51], s[0:1], 0x40
	s_load_dwordx16 s[52:67], s[0:1], 0x80
	v_readlane_b32 s0, v238, 0
	s_lshr_b32 s91, s76, 6
	s_lshl_b32 s3, s0, 3
	s_add_i32 s80, s3, s91
	s_lshl_b32 s78, s72, 3
	v_readlane_b32 s1, v238, 1
	s_setprio 0
	s_cmp_lt_i32 s74, 1
	s_cselect_b64 s[0:1], -1, 0
	s_cmp_gt_i32 s75, 0
	s_cselect_b64 s[4:5], -1, 0
	s_and_b64 s[0:1], s[0:1], s[4:5]
	s_andn2_b64 vcc, exec, s[0:1]
	v_and_b32_e32 v130, 63, v128
	s_cbranch_vccnz .LBB0_112
	v_writelane_b32 v238, s34, 2
	s_mov_b64 s[82:83], s[94:95]
	s_cmpk_gt_i32 s80, 0x61ff
	v_writelane_b32 v238, s35, 3
	v_writelane_b32 v238, s33, 4
	s_mov_b32 s33, s76
	v_writelane_b32 v238, s92, 6
	s_mov_b32 s76, s96
	s_nop 0
	v_writelane_b32 v238, s93, 7
	s_cbranch_scc1 .LBB0_67
	v_lshlrev_b32_e32 v3, 3, v128
	s_lshl_b32 s0, s91, 14
	v_lshrrev_b32_e32 v28, 3, v130
	v_and_b32_e32 v6, 56, v3
	s_add_i32 s0, s0, 0
	v_lshrrev_b32_e32 v2, 5, v130
	v_mul_u32_u24_e32 v3, 0x84, v6
	v_lshlrev_b32_e32 v8, 2, v28
	s_movk_i32 s4, 0x84
	v_add3_u32 v29, s0, v3, v8
	v_or_b32_e32 v3, 2, v2
	v_mov_b32_e32 v8, 0x318
	v_mad_u32_u24 v34, v3, s4, v8
	v_mov_b32_e32 v8, 0x738
	s_add_u32 s79, s70, 0x100000
	v_mad_u32_u24 v35, v3, s4, v8
	v_mov_b32_e32 v8, 0xb58
	s_addc_u32 s81, s71, 0
	v_mad_u32_u24 v36, v3, s4, v8
	v_mov_b32_e32 v8, 0xf78
	s_waitcnt lgkmcnt(0)
	s_cmp_lg_u64 s[20:21], 0
	v_and_b32_e32 v4, 31, v128
	v_mad_u32_u24 v37, v3, s4, v8
	s_cselect_b64 s[6:7], -1, 0
	s_cmp_lg_u64 s[18:19], 0
	v_readlane_b32 s4, v238, 0
	v_lshl_add_u32 v1, v4, 2, s0
	v_mul_u32_u24_e32 v7, 0x84, v2
	s_cselect_b64 s[8:9], -1, 0
	s_mov_b32 s10, s4
	s_lshl_b32 s0, s4, 8
	s_lshl_b32 s4, s91, 5
	v_mov_b32_e32 v5, 0
	s_add_i32 s92, s0, s4
	s_lshl_b32 s0, s10, 4
	s_lshl_b32 s4, s91, 1
	v_add_u32_e32 v38, v1, v7
	s_mov_b32 s1, 0
	v_or_b32_e32 v30, 8, v28
	v_or_b32_e32 v31, 16, v28
	v_or_b32_e32 v32, 24, v28
	v_mul_u32_u24_e32 v33, 0x84, v3
	v_mov_b32_e32 v3, v5
	s_lshl_b32 s93, s72, 8
	s_add_i32 s94, s0, s4
	s_lshl_b32 s95, s72, 4
	s_movk_i32 s96, 0x3000
	v_lshlrev_b32_e32 v4, 2, v4
	v_add_u32_e32 v39, 0x400, v38
	v_add_u32_e32 v40, 0x800, v38
	v_add_u32_e32 v41, 0xc00, v38
	v_add_u32_e32 v42, 0x1000, v38
	v_add_u32_e32 v43, 0x1400, v38
	v_add_u32_e32 v44, 0x1800, v38
	v_add_u32_e32 v45, 0x1c00, v38
	v_lshlrev_b32_e32 v6, 1, v6
	s_mov_b32 s97, s80
	v_readlane_b32 s5, v238, 1
	s_branch .LBB0_15

.LBB0_112:
	s_setprio 0
	s_cmp_lt_i32 s74, 2
	s_cselect_b64 s[0:1], -1, 0
	s_cmp_gt_i32 s75, 1
	s_cselect_b64 s[4:5], -1, 0
	s_and_b64 s[0:1], s[0:1], s[4:5]
	s_andn2_b64 vcc, exec, s[0:1]
	s_cbranch_vccnz .LBB0_187
	v_readlane_b32 s0, v238, 0
	s_cmpk_gt_i32 s0, 0xff
	v_readlane_b32 s1, v238, 1
	s_cbranch_scc1 .LBB0_128
	v_mbcnt_lo_u32_b32 v2, -1, 0
	v_lshlrev_b32_e32 v8, 14, v130
	v_mov_b32_e32 v9, 0
	v_lshlrev_b32_e32 v4, 4, v128
	v_mbcnt_hi_u32_b32 v2, -1, v2
	s_waitcnt lgkmcnt(0)
	v_lshl_add_u64 v[10:11], s[56:57], 0, v[8:9]
	v_and_b32_e32 v8, 0xf0, v4
	v_and_b32_e32 v7, 64, v2
	v_lshl_add_u64 v[0:1], s[70:71], 0, v[8:9]
	v_add_u32_e32 v5, 0, v8
	v_add_u32_e32 v7, 64, v7
	v_xor_b32_e32 v8, 1, v2
	v_cmp_lt_i32_e32 vcc, v8, v7
	s_add_u32 s12, s70, 0x6600000
	s_addc_u32 s13, s71, 0
	v_cndmask_b32_e32 v8, v2, v8, vcc
	v_lshlrev_b32_e32 v23, 2, v8
	v_xor_b32_e32 v8, 2, v2
	v_cmp_lt_i32_e32 vcc, v8, v7
	s_lshl_b32 s0, s91, 9
	s_add_i32 s18, s0, 0
	v_cndmask_b32_e32 v8, v2, v8, vcc
	v_lshlrev_b32_e32 v24, 2, v8
	v_xor_b32_e32 v8, 4, v2
	v_cmp_lt_i32_e32 vcc, v8, v7
	s_mov_b64 s[0:1], 0x6400000
	v_lshl_add_u64 v[0:1], v[0:1], 0, s[0:1]
	v_cndmask_b32_e32 v8, v2, v8, vcc
	v_lshlrev_b32_e32 v25, 2, v8
	v_xor_b32_e32 v8, 8, v2
	v_cmp_lt_i32_e32 vcc, v8, v7
	s_mov_b64 s[0:1], 0x6404000
	s_lshl_b32 s6, s91, 14
	v_cndmask_b32_e32 v8, v2, v8, vcc
	v_lshlrev_b32_e32 v26, 2, v8
	v_xor_b32_e32 v8, 16, v2
	v_cmp_lt_i32_e32 vcc, v8, v7
	v_lshlrev_b32_e32 v3, 2, v130
	s_add_i32 s18, s18, 0x24400
	v_cndmask_b32_e32 v8, v2, v8, vcc
	v_lshlrev_b32_e32 v27, 2, v8
	v_xor_b32_e32 v8, 32, v2
	v_cmp_lt_i32_e32 vcc, v8, v7
	v_mul_u32_u24_e32 v6, 0x110, v130
	v_add_u32_e32 v22, s18, v3
	v_cndmask_b32_e32 v2, v2, v8, vcc
	v_and_b32_e32 v8, 0x3f00, v4
	v_mov_b32_e32 v4, 0x800
	v_lshl_add_u32 v4, v128, 2, v4
	v_and_b32_e32 v4, 0x1fc0, v4
	v_lshl_add_u64 v[12:13], v[0:1], 0, v[8:9]
	v_lshlrev_b32_e32 v8, 2, v4
	v_lshl_add_u64 v[14:15], v[0:1], 0, v[8:9]
	v_add_u32_e32 v1, 0x200, v128
	v_lshrrev_b32_e32 v7, 4, v1
	v_and_b32_e32 v1, 15, v128
	v_lshrrev_b32_e32 v0, 4, v128
	v_lshlrev_b32_e32 v18, 4, v1
	v_lshl_or_b32 v8, v0, 8, v18
	v_mul_u32_u24_e32 v4, 0x110, v0
	v_lshl_add_u64 v[0:1], s[70:71], 0, v[8:9]
	v_lshl_or_b32 v8, v7, 8, v18
	v_lshl_add_u64 v[16:17], v[0:1], 0, s[0:1]
	v_lshl_add_u64 v[0:1], s[70:71], 0, v[8:9]
	v_lshl_add_u64 v[18:19], v[0:1], 0, s[0:1]
	s_add_i32 s0, s6, 0
	v_add_u32_e32 v0, s0, v3
	s_mul_i32 s0, s80, 0x2020
	s_mul_hi_i32 s1, s80, 0x2020
	s_add_u32 s0, s70, s0
	v_lshlrev_b32_e32 v28, 2, v2
	v_add_u32_e32 v2, 0xfff, v130
	v_cmp_ne_u32_e32 vcc, 0, v130
	v_lshlrev_b32_e32 v8, 1, v130
	s_addc_u32 s1, s71, s1
	v_cndmask_b32_e32 v2, 0, v2, vcc
	v_mul_u32_u24_e32 v33, 0x110, v7
	v_add_u32_e32 v29, 0x4400, v0
	v_lshl_add_u64 v[0:1], s[0:1], 0, v[8:9]
	s_mov_b64 s[0:1], 0x6601100
	v_cmp_gt_u32_e64 s[4:5], 17, v130
	v_sub_u32_e32 v30, 0, v130
	v_lshl_add_u64 v[20:21], v[0:1], 0, s[0:1]
	s_mul_hi_i32 s1, s78, 0x2020
	s_mul_i32 s0, s78, 0x2020
	v_mov_b32_e32 v31, 0x3f2aaaab
	v_add_u32_e32 v32, v5, v4
	v_add_u32_e32 v33, v5, v33
	v_add_u32_e32 v34, 0, v6
	s_mov_b32 s19, 0xc4ffe000
	s_mov_b64 s[6:7], 0x200
	v_lshlrev_b32_e32 v35, 1, v2
	s_branch .LBB0_116

.LBB0_194:
	s_waitcnt lgkmcnt(0)
	s_add_u32 s18, s70, 0x1b700000
	s_addc_u32 s19, s71, 0
	s_add_u32 s14, s70, 0x7700000
	s_addc_u32 s15, s71, 0
	s_add_u32 s16, s70, 0xf700000
	s_addc_u32 s17, s71, 0
	s_setprio 0
	s_cmp_lt_i32 s74, 3
	s_cselect_b64 s[0:1], -1, 0
	s_cmp_gt_i32 s75, 2
	s_cselect_b64 s[4:5], -1, 0
	s_and_b64 s[0:1], s[0:1], s[4:5]
	s_andn2_b64 vcc, exec, s[0:1]
	v_lshrrev_b32_e32 v129, 8, v128
	s_cbranch_vccnz .LBB0_303
	v_lshlrev_b32_e32 v8, 2, v128
	s_ashr_i32 s3, s2, 31
	v_add_u32_e32 v0, 0, v8
	s_ashr_i32 s56, s72, 31
	s_mov_b32 s57, s72
	v_and_b32_e32 v4, 0xff, v128
	v_add_u32_e32 v5, 0xfffffe00, v128
	v_add_u32_e32 v6, 0x20000, v0
	v_lshrrev_b32_e32 v7, 8, v128
	s_mov_b64 s[0:1], 0
	v_mov_b64_e32 v[0:1], s[2:3]
	s_mov_b64 s[4:5], 0x600
	s_mov_b32 s10, 0x2aaaaaab
	s_movk_i32 s11, 0x60
	v_mov_b32_e32 v9, 0x358637bd
	s_movk_i32 s12, 0x8ff
	v_mov_b32_e32 v10, 0xc0
	v_mov_b32_e32 v11, 0xc1
	v_and_b32_e32 v110, 0xff, v128
	s_lshr_b32 s98, s91, 2
	v_mov_b32_e32 v111, 0x358637bd
	s_mul_i32 s99, s98, s72
	s_add_i32 s99, s99, s2
	s_cmp_lt_u32 s99, 0x600
	s_cselect_b32 s99, s99, s2
	s_and_b32 s100, s99, 7
	s_mul_i32 s100, s100, 0xc0
	s_lshr_b32 s101, s99, 3
	s_add_i32 s100, s100, s101
	s_mul_hi_u32 s101, s100, 0x2aaaaab
	s_lshl_b32 s101, s101, 3
	s_and_b32 s100, s100, 7
	s_or_b32 s101, s101, s100
	s_lshl_b32 s101, s101, 8
	v_add_u32_e32 v108, s101, v110
	v_lshlrev_b32_e32 v108, 6, v108
	v_mov_b32_e32 v109, 0
	v_lshl_add_u64 v[108:109], s[18:19], 0, v[108:109]
	global_load_dwordx4 v[12:15], v[108:109], off
	global_load_dwordx4 v[16:19], v[108:109], off offset:16
	global_load_dwordx4 v[20:23], v[108:109], off offset:32
	global_load_dwordx4 v[24:27], v[108:109], off offset:48
	s_add_i32 s98, s98, 2
	s_mul_i32 s99, s98, s72
	s_add_i32 s99, s99, s2
	s_cmp_lt_u32 s99, 0x600
	s_cselect_b32 s99, s99, s2
	s_and_b32 s100, s99, 7
	s_mul_i32 s100, s100, 0xc0
	s_lshr_b32 s101, s99, 3
	s_add_i32 s100, s100, s101
	s_mul_hi_u32 s101, s100, 0x2aaaaab
	s_lshl_b32 s101, s101, 3
	s_and_b32 s100, s100, 7
	s_or_b32 s101, s101, s100
	s_lshl_b32 s101, s101, 8
	v_add_u32_e32 v108, s101, v110
	v_lshlrev_b32_e32 v108, 6, v108
	v_mov_b32_e32 v109, 0
	v_lshl_add_u64 v[108:109], s[18:19], 0, v[108:109]
	global_load_dwordx4 v[28:31], v[108:109], off
	global_load_dwordx4 v[32:35], v[108:109], off offset:16
	global_load_dwordx4 v[36:39], v[108:109], off offset:32
	global_load_dwordx4 v[40:43], v[108:109], off offset:48
	s_add_i32 s98, s98, 2
	s_mul_i32 s99, s98, s72
	s_add_i32 s99, s99, s2
	s_cmp_lt_u32 s99, 0x600
	s_cselect_b32 s99, s99, s2
	s_and_b32 s100, s99, 7
	s_mul_i32 s100, s100, 0xc0
	s_lshr_b32 s101, s99, 3
	s_add_i32 s100, s100, s101
	s_mul_hi_u32 s101, s100, 0x2aaaaab
	s_lshl_b32 s101, s101, 3
	s_and_b32 s100, s100, 7
	s_or_b32 s101, s101, s100
	s_lshl_b32 s101, s101, 8
	v_add_u32_e32 v108, s101, v110
	v_lshlrev_b32_e32 v108, 6, v108
	v_mov_b32_e32 v109, 0
	v_lshl_add_u64 v[108:109], s[18:19], 0, v[108:109]
	global_load_dwordx4 v[44:47], v[108:109], off
	global_load_dwordx4 v[48:51], v[108:109], off offset:16
	global_load_dwordx4 v[52:55], v[108:109], off offset:32
	global_load_dwordx4 v[56:59], v[108:109], off offset:48
	s_add_i32 s98, s98, 2
	v_lshlrev_b32_e32 v112, 2, v128
	v_add_u32_e32 v112, 0x20000, v112
	s_waitcnt vmcnt(8)
	v_pk_add_f32 v[114:115], v[14:15], v[18:19]
	v_pk_add_f32 v[116:117], v[12:13], v[16:17]
	v_pk_add_f32 v[118:119], v[22:23], v[26:27]
	v_pk_add_f32 v[120:121], v[20:21], v[24:25]
	v_pk_add_f32 v[114:115], v[114:115], v[118:119]
	v_pk_add_f32 v[116:117], v[116:117], v[120:121]
	v_add_f32_e32 v116, v117, v116
	v_add_f32_e32 v114, v114, v115
	v_add_f32_e32 v114, v116, v114
	v_fmamk_f32 v114, v114, 0x3a800000, v111
	v_rsq_f32_e32 v114, v114
	ds_write_b32 v112, v114
	s_waitcnt vmcnt(4)
	v_pk_add_f32 v[114:115], v[30:31], v[34:35]
	v_pk_add_f32 v[116:117], v[28:29], v[32:33]
	v_pk_add_f32 v[118:119], v[38:39], v[42:43]
	v_pk_add_f32 v[120:121], v[36:37], v[40:41]
	v_pk_add_f32 v[114:115], v[114:115], v[118:119]
	v_pk_add_f32 v[116:117], v[116:117], v[120:121]
	v_add_f32_e32 v116, v117, v116
	v_add_f32_e32 v114, v114, v115
	v_add_f32_e32 v114, v116, v114
	v_fmamk_f32 v114, v114, 0x3a800000, v111
	v_rsq_f32_e32 v114, v114
	ds_write_b32 v112, v114 offset:2048
	s_waitcnt vmcnt(0)
	v_pk_add_f32 v[114:115], v[46:47], v[50:51]
	v_pk_add_f32 v[116:117], v[44:45], v[48:49]
	v_pk_add_f32 v[118:119], v[54:55], v[58:59]
	v_pk_add_f32 v[120:121], v[52:53], v[56:57]
	v_pk_add_f32 v[114:115], v[114:115], v[118:119]
	v_pk_add_f32 v[116:117], v[116:117], v[120:121]
	v_add_f32_e32 v116, v117, v116
	v_add_f32_e32 v114, v114, v115
	v_add_f32_e32 v114, v116, v114
	v_fmamk_f32 v114, v114, 0x3a800000, v111
	v_rsq_f32_e32 v114, v114
	ds_write_b32 v112, v114 offset:4096

.LBB0_210:
	s_ashr_i32 s41, s40, 31
	s_lshl_b64 s[12:13], s[40:41], 19
	s_add_u32 s42, s14, s12
	s_addc_u32 s43, s15, s13
	s_and_b64 s[12:13], s[4:5], exec
	s_cselect_b32 s7, s43, s51
	s_cselect_b32 s8, s42, s50
	s_ashr_i32 s29, s28, 31
	s_lshl_b64 s[12:13], s[28:29], 19
	s_add_u32 s48, s59, s12
	s_addc_u32 s49, s62, s13
	s_and_b64 s[12:13], s[4:5], exec
	s_cselect_b32 s12, s49, s53
	s_cselect_b32 s13, s48, s52
	s_add_u32 s50, s50, 0x40080
	s_addc_u32 s51, s51, 0
	s_add_u32 s29, s52, 0x100
	s_addc_u32 s41, s53, 0
	s_mov_b32 s86, -2
	s_waitcnt lgkmcnt(0)
	s_setprio 0
	s_cmp_lg_u32 s84, 1
	s_cselect_b32 s100, s99, 0
	s_cmp_lg_u32 s100, 0
	s_cbranch_scc0 .Lmy_nobar2_2
	s_barrier

.Lmy_nobar_2:
	s_cmp_eq_u32 s99, 0
	s_cbranch_scc0 .Lmy_pr_2
	s_setprio 1

.LBB0_303:
	s_add_u32 s20, s70, 0xb700000
	s_addc_u32 s21, s71, 0
	s_setprio 0
	s_cmp_lt_i32 s74, 4
	s_cselect_b64 s[0:1], -1, 0
	s_cmp_gt_i32 s75, 3
	s_cselect_b64 s[4:5], -1, 0
	s_and_b64 s[0:1], s[0:1], s[4:5]
	s_andn2_b64 vcc, exec, s[0:1]
	v_readlane_b32 s0, v238, 0
	v_readlane_b32 s1, v238, 1
	s_nop 0
	v_lshl_add_u32 v156, s0, 9, v128
	s_cbranch_vccnz .LBB0_365
	v_readlane_b32 s0, v238, 0
	v_readlane_b32 s1, v238, 1
	s_nop 0
	v_lshl_add_u32 v20, s0, 9, v128
	s_mov_b32 s0, 0x400000
	v_cmp_gt_i32_e32 vcc, s0, v20
	s_and_saveexec_b64 s[0:1], vcc
	s_cbranch_execz .LBB0_311
	s_add_u32 s4, s70, 0x13700000
	s_addc_u32 s5, s71, 0
	s_lshl_b32 s3, s72, 9
	s_add_u32 s6, s24, 0x1000
	s_addc_u32 s7, s25, 0
	v_readlane_b32 s10, v238, 0
	s_add_u32 s8, s24, 0x2000
	v_lshlrev_b32_e32 v0, 3, v128
	v_readlane_b32 s11, v238, 1
	s_addc_u32 s9, s25, 0
	v_lshl_add_u32 v21, s10, 12, v0
	s_lshl_b32 s12, s72, 12
	s_mov_b64 s[10:11], 0
	s_movk_i32 s13, 0x7ff
	s_mov_b32 s26, 0x3fffff
	s_branch .LBB0_307

.LBB0_365:
	s_setprio 0
	s_cmp_lt_i32 s74, 5
	s_cselect_b64 s[0:1], -1, 0
	s_cmp_gt_i32 s75, 4
	s_cselect_b64 s[4:5], -1, 0
	s_and_b64 s[0:1], s[0:1], s[4:5]
	s_andn2_b64 vcc, exec, s[0:1]
	s_cbranch_vccnz .LBB0_462
	s_cmpk_lt_i32 s2, 0x200
	s_cselect_b64 s[4:5], -1, 0
	s_cmpk_gt_i32 s2, 0x1ff
	v_readfirstlane_b32 s6, v128
	s_cbranch_scc0 .LBB0_369
	s_andn2_b64 vcc, exec, s[4:5]
	s_cbranch_vccz .LBB0_374

.LBB0_385:
	s_ashr_i32 s29, s28, 31
	s_lshl_b64 s[12:13], s[28:29], 19
	s_add_u32 s40, s20, s12
	s_addc_u32 s41, s21, s13
	s_and_b64 s[12:13], s[6:7], exec
	s_cselect_b32 s12, s41, s51
	s_cselect_b32 s13, s40, s50
	s_ashr_i32 s27, s26, 31
	s_lshl_b64 s[34:35], s[26:27], 19
	s_add_u32 s42, s3, s34
	s_addc_u32 s43, s56, s35
	s_and_b64 s[34:35], s[6:7], exec
	s_cselect_b32 s27, s43, s53
	s_cselect_b32 s29, s42, s52
	s_add_u32 s50, s50, 0x40080
	s_addc_u32 s51, s51, 0
	s_add_u32 s49, s52, 0x100
	s_addc_u32 s77, s53, 0
	s_mov_b32 s85, -2
	s_waitcnt lgkmcnt(0)
	s_setprio 0
	s_cmp_lg_u32 s84, 1
	s_cselect_b32 s100, s99, 0
	s_cmp_lg_u32 s100, 0
	s_cbranch_scc0 .Lmy_nobar2_4
	s_barrier

.LBB0_462:
	s_setprio 0
	s_cmp_lt_i32 s74, 6
	s_cselect_b64 s[0:1], -1, 0
	s_cmp_gt_i32 s75, 5
	s_cselect_b64 s[4:5], -1, 0
	s_and_b64 s[0:1], s[0:1], s[4:5]
	s_andn2_b64 vcc, exec, s[0:1]
	s_cbranch_vccnz .LBB0_537
	v_lshlrev_b32_e32 v8, 2, v128
	s_ashr_i32 s3, s2, 31
	v_add_u32_e32 v0, 0, v8
	s_ashr_i32 s52, s72, 31
	s_mov_b32 s53, s72
	v_and_b32_e32 v4, 0xff, v128
	v_add_u32_e32 v5, 0xfffffe00, v128
	v_add_u32_e32 v6, 0x20000, v0
	v_lshrrev_b32_e32 v7, 8, v128
	s_mov_b64 s[0:1], 0
	s_waitcnt lgkmcnt(0)
	v_mov_b64_e32 v[0:1], s[2:3]
	s_mov_b64 s[4:5], 0xb00
	s_mov_b32 s10, 0x2e8ba2e9
	s_movk_i32 s11, 0xb0
	v_mov_b32_e32 v9, 0x358637bd
	s_movk_i32 s12, 0x8ff
	v_mov_b32_e32 v10, 0x160
	v_mov_b32_e32 v11, 0x161
	v_and_b32_e32 v110, 0xff, v128
	s_lshr_b32 s98, s91, 2
	v_mov_b32_e32 v111, 0x358637bd
	s_mul_i32 s99, s98, s72
	s_add_i32 s99, s99, s2
	s_cmp_lt_u32 s99, 0xb00
	s_cselect_b32 s99, s99, s2
	s_and_b32 s100, s99, 7
	s_mul_i32 s100, s100, 0x160
	s_lshr_b32 s101, s99, 3
	s_add_i32 s100, s100, s101
	s_mul_hi_u32 s101, s100, 0x1745d18
	s_lshl_b32 s101, s101, 3
	s_and_b32 s100, s100, 7
	s_or_b32 s101, s101, s100
	s_lshl_b32 s101, s101, 8
	v_add_u32_e32 v108, s101, v110
	v_lshlrev_b32_e32 v108, 6, v108
	v_mov_b32_e32 v109, 0
	v_lshl_add_u64 v[108:109], s[18:19], 0, v[108:109]
	global_load_dwordx4 v[12:15], v[108:109], off
	global_load_dwordx4 v[16:19], v[108:109], off offset:16
	global_load_dwordx4 v[20:23], v[108:109], off offset:32
	global_load_dwordx4 v[24:27], v[108:109], off offset:48
	s_add_i32 s98, s98, 2
	s_mul_i32 s99, s98, s72
	s_add_i32 s99, s99, s2
	s_cmp_lt_u32 s99, 0xb00
	s_cselect_b32 s99, s99, s2
	s_and_b32 s100, s99, 7
	s_mul_i32 s100, s100, 0x160
	s_lshr_b32 s101, s99, 3
	s_add_i32 s100, s100, s101
	s_mul_hi_u32 s101, s100, 0x1745d18
	s_lshl_b32 s101, s101, 3
	s_and_b32 s100, s100, 7
	s_or_b32 s101, s101, s100
	s_lshl_b32 s101, s101, 8
	v_add_u32_e32 v108, s101, v110
	v_lshlrev_b32_e32 v108, 6, v108
	v_mov_b32_e32 v109, 0
	v_lshl_add_u64 v[108:109], s[18:19], 0, v[108:109]
	global_load_dwordx4 v[28:31], v[108:109], off
	global_load_dwordx4 v[32:35], v[108:109], off offset:16
	global_load_dwordx4 v[36:39], v[108:109], off offset:32
	global_load_dwordx4 v[40:43], v[108:109], off offset:48
	s_add_i32 s98, s98, 2
	s_mul_i32 s99, s98, s72
	s_add_i32 s99, s99, s2
	s_cmp_lt_u32 s99, 0xb00
	s_cselect_b32 s99, s99, s2
	s_and_b32 s100, s99, 7
	s_mul_i32 s100, s100, 0x160
	s_lshr_b32 s101, s99, 3
	s_add_i32 s100, s100, s101
	s_mul_hi_u32 s101, s100, 0x1745d18
	s_lshl_b32 s101, s101, 3
	s_and_b32 s100, s100, 7
	s_or_b32 s101, s101, s100
	s_lshl_b32 s101, s101, 8
	v_add_u32_e32 v108, s101, v110
	v_lshlrev_b32_e32 v108, 6, v108
	v_mov_b32_e32 v109, 0
	v_lshl_add_u64 v[108:109], s[18:19], 0, v[108:109]
	global_load_dwordx4 v[44:47], v[108:109], off
	global_load_dwordx4 v[48:51], v[108:109], off offset:16
	global_load_dwordx4 v[52:55], v[108:109], off offset:32
	global_load_dwordx4 v[56:59], v[108:109], off offset:48
	s_add_i32 s98, s98, 2
	s_mul_i32 s99, s98, s72
	s_add_i32 s99, s99, s2
	s_cmp_lt_u32 s99, 0xb00
	s_cselect_b32 s99, s99, s2
	s_and_b32 s100, s99, 7
	s_mul_i32 s100, s100, 0x160
	s_lshr_b32 s101, s99, 3
	s_add_i32 s100, s100, s101
	s_mul_hi_u32 s101, s100, 0x1745d18
	s_lshl_b32 s101, s101, 3
	s_and_b32 s100, s100, 7
	s_or_b32 s101, s101, s100
	s_lshl_b32 s101, s101, 8
	v_add_u32_e32 v108, s101, v110
	v_lshlrev_b32_e32 v108, 6, v108
	v_mov_b32_e32 v109, 0
	v_lshl_add_u64 v[108:109], s[18:19], 0, v[108:109]
	global_load_dwordx4 v[60:63], v[108:109], off
	global_load_dwordx4 v[64:67], v[108:109], off offset:16
	global_load_dwordx4 v[68:71], v[108:109], off offset:32
	global_load_dwordx4 v[72:75], v[108:109], off offset:48
	s_add_i32 s98, s98, 2
	s_mul_i32 s99, s98, s72
	s_add_i32 s99, s99, s2
	s_cmp_lt_u32 s99, 0xb00
	s_cselect_b32 s99, s99, s2
	s_and_b32 s100, s99, 7
	s_mul_i32 s100, s100, 0x160
	s_lshr_b32 s101, s99, 3
	s_add_i32 s100, s100, s101
	s_mul_hi_u32 s101, s100, 0x1745d18
	s_lshl_b32 s101, s101, 3
	s_and_b32 s100, s100, 7
	s_or_b32 s101, s101, s100
	s_lshl_b32 s101, s101, 8
	v_add_u32_e32 v108, s101, v110
	v_lshlrev_b32_e32 v108, 6, v108
	v_mov_b32_e32 v109, 0
	v_lshl_add_u64 v[108:109], s[18:19], 0, v[108:109]
	global_load_dwordx4 v[76:79], v[108:109], off
	global_load_dwordx4 v[80:83], v[108:109], off offset:16
	global_load_dwordx4 v[84:87], v[108:109], off offset:32
	global_load_dwordx4 v[88:91], v[108:109], off offset:48
	s_add_i32 s98, s98, 2
	s_mul_i32 s99, s98, s72
	s_add_i32 s99, s99, s2
	s_cmp_lt_u32 s99, 0xb00
	s_cselect_b32 s99, s99, s2
	s_and_b32 s100, s99, 7
	s_mul_i32 s100, s100, 0x160
	s_lshr_b32 s101, s99, 3
	s_add_i32 s100, s100, s101
	s_mul_hi_u32 s101, s100, 0x1745d18
	s_lshl_b32 s101, s101, 3
	s_and_b32 s100, s100, 7
	s_or_b32 s101, s101, s100
	s_lshl_b32 s101, s101, 8
	v_add_u32_e32 v108, s101, v110
	v_lshlrev_b32_e32 v108, 6, v108
	v_mov_b32_e32 v109, 0
	v_lshl_add_u64 v[108:109], s[18:19], 0, v[108:109]
	global_load_dwordx4 v[92:95], v[108:109], off
	global_load_dwordx4 v[96:99], v[108:109], off offset:16
	global_load_dwordx4 v[100:103], v[108:109], off offset:32
	global_load_dwordx4 v[104:107], v[108:109], off offset:48
	s_add_i32 s98, s98, 2
	v_lshlrev_b32_e32 v112, 2, v128
	v_add_u32_e32 v112, 0x20000, v112
	s_waitcnt vmcnt(20)
	v_pk_add_f32 v[114:115], v[14:15], v[18:19]
	v_pk_add_f32 v[116:117], v[12:13], v[16:17]
	v_pk_add_f32 v[118:119], v[22:23], v[26:27]
	v_pk_add_f32 v[120:121], v[20:21], v[24:25]
	v_pk_add_f32 v[114:115], v[114:115], v[118:119]
	v_pk_add_f32 v[116:117], v[116:117], v[120:121]
	v_add_f32_e32 v116, v117, v116
	v_add_f32_e32 v114, v114, v115
	v_add_f32_e32 v114, v116, v114
	v_fmamk_f32 v114, v114, 0x3a800000, v111
	v_rsq_f32_e32 v114, v114
	ds_write_b32 v112, v114
	s_waitcnt vmcnt(16)
	v_pk_add_f32 v[114:115], v[30:31], v[34:35]
	v_pk_add_f32 v[116:117], v[28:29], v[32:33]
	v_pk_add_f32 v[118:119], v[38:39], v[42:43]
	v_pk_add_f32 v[120:121], v[36:37], v[40:41]
	v_pk_add_f32 v[114:115], v[114:115], v[118:119]
	v_pk_add_f32 v[116:117], v[116:117], v[120:121]
	v_add_f32_e32 v116, v117, v116
	v_add_f32_e32 v114, v114, v115
	v_add_f32_e32 v114, v116, v114
	v_fmamk_f32 v114, v114, 0x3a800000, v111
	v_rsq_f32_e32 v114, v114
	ds_write_b32 v112, v114 offset:2048
	s_waitcnt vmcnt(12)
	v_pk_add_f32 v[114:115], v[46:47], v[50:51]
	v_pk_add_f32 v[116:117], v[44:45], v[48:49]
	v_pk_add_f32 v[118:119], v[54:55], v[58:59]
	v_pk_add_f32 v[120:121], v[52:53], v[56:57]
	v_pk_add_f32 v[114:115], v[114:115], v[118:119]
	v_pk_add_f32 v[116:117], v[116:117], v[120:121]
	v_add_f32_e32 v116, v117, v116
	v_add_f32_e32 v114, v114, v115
	v_add_f32_e32 v114, v116, v114
	v_fmamk_f32 v114, v114, 0x3a800000, v111
	v_rsq_f32_e32 v114, v114
	ds_write_b32 v112, v114 offset:4096
	s_waitcnt vmcnt(8)
	v_pk_add_f32 v[114:115], v[62:63], v[66:67]
	v_pk_add_f32 v[116:117], v[60:61], v[64:65]
	v_pk_add_f32 v[118:119], v[70:71], v[74:75]
	v_pk_add_f32 v[120:121], v[68:69], v[72:73]
	v_pk_add_f32 v[114:115], v[114:115], v[118:119]
	v_pk_add_f32 v[116:117], v[116:117], v[120:121]
	v_add_f32_e32 v116, v117, v116
	v_add_f32_e32 v114, v114, v115
	v_add_f32_e32 v114, v116, v114
	v_fmamk_f32 v114, v114, 0x3a800000, v111
	v_rsq_f32_e32 v114, v114
	ds_write_b32 v112, v114 offset:6144
	s_waitcnt vmcnt(4)
	v_pk_add_f32 v[114:115], v[78:79], v[82:83]
	v_pk_add_f32 v[116:117], v[76:77], v[80:81]
	v_pk_add_f32 v[118:119], v[86:87], v[90:91]
	v_pk_add_f32 v[120:121], v[84:85], v[88:89]
	v_pk_add_f32 v[114:115], v[114:115], v[118:119]
	v_pk_add_f32 v[116:117], v[116:117], v[120:121]
	v_add_f32_e32 v116, v117, v116
	v_add_f32_e32 v114, v114, v115
	v_add_f32_e32 v114, v116, v114
	v_fmamk_f32 v114, v114, 0x3a800000, v111
	v_rsq_f32_e32 v114, v114
	ds_write_b32 v112, v114 offset:8192
	s_waitcnt vmcnt(0)
	v_pk_add_f32 v[114:115], v[94:95], v[98:99]
	v_pk_add_f32 v[116:117], v[92:93], v[96:97]
	v_pk_add_f32 v[118:119], v[102:103], v[106:107]
	v_pk_add_f32 v[120:121], v[100:101], v[104:105]
	v_pk_add_f32 v[114:115], v[114:115], v[118:119]
	v_pk_add_f32 v[116:117], v[116:117], v[120:121]
	v_add_f32_e32 v116, v117, v116
	v_add_f32_e32 v114, v114, v115
	v_add_f32_e32 v114, v116, v114
	v_fmamk_f32 v114, v114, 0x3a800000, v111
	v_rsq_f32_e32 v114, v114
	ds_write_b32 v112, v114 offset:10240

.LBB0_475:
	s_ashr_i32 s23, s22, 31
	s_lshl_b64 s[26:27], s[22:23], 19
	s_add_u32 s26, s14, s26
	s_addc_u32 s27, s15, s27
	s_and_b64 s[28:29], s[4:5], exec
	s_cselect_b32 s23, s27, s43
	s_cselect_b32 s81, s26, s42
	s_ashr_i32 s11, s10, 31
	s_lshl_b64 s[28:29], s[10:11], 19
	s_add_u32 s28, s55, s28
	s_addc_u32 s29, s56, s29
	s_and_b64 s[34:35], s[4:5], exec
	s_cselect_b32 s11, s29, s49
	s_cselect_b32 s82, s28, s48
	s_add_u32 s42, s42, 0x40080
	s_addc_u32 s43, s43, 0
	s_add_u32 s83, s48, 0x100
	s_addc_u32 s84, s49, 0
	s_mov_b32 s85, -2
	s_setprio 0
	s_cmp_lg_u32 s77, 1
	s_cselect_b32 s100, s99, 0
	s_cmp_lg_u32 s100, 0
	s_cbranch_scc0 .Lmy_nobar2_5
	s_barrier

.LBB0_537:
	s_setprio 0
	s_cmp_lt_i32 s74, 7
	s_cselect_b64 s[0:1], -1, 0
	s_cmp_gt_i32 s75, 6
	s_cselect_b64 s[4:5], -1, 0
	s_and_b64 s[0:1], s[0:1], s[4:5]
	s_andn2_b64 vcc, exec, s[0:1]
	s_cbranch_vccnz .LBB0_638
	s_cmpk_lt_i32 s2, 0x200
	s_cselect_b64 s[0:1], -1, 0
	s_cmpk_gt_i32 s2, 0x1ff
	v_readfirstlane_b32 s6, v128
	s_cbranch_scc0 .LBB0_541
	s_andn2_b64 vcc, exec, s[0:1]
	s_cbranch_vccz .LBB0_546

.LBB0_561:
	s_add_u32 s40, s40, 0xb0080
	s_addc_u32 s41, s41, 0
	s_add_u32 s13, s42, 0x100
	s_addc_u32 s77, s43, 0
	s_mov_b32 s81, -2
	s_waitcnt lgkmcnt(0)
	s_setprio 0
	s_cmp_lg_u32 s66, 1
	s_cselect_b32 s100, s99, 0
	s_cmp_lg_u32 s100, 0
	s_cbranch_scc0 .Lmy_nobar2_6
	s_barrier

.LBB0_638:
	s_setprio 0
	s_cmp_lt_i32 s74, 8
	s_cselect_b64 s[0:1], -1, 0
	s_cmp_gt_i32 s75, 7
	s_cselect_b64 s[4:5], -1, 0
	s_and_b64 s[0:1], s[0:1], s[4:5]
	s_andn2_b64 vcc, exec, s[0:1]
	s_cbranch_vccnz .LBB0_779
	v_lshlrev_b32_e32 v8, 2, v128
	s_ashr_i32 s3, s2, 31
	v_add_u32_e32 v0, 0, v8
	s_ashr_i32 s58, s72, 31
	s_mov_b32 s59, s72
	v_and_b32_e32 v4, 0xff, v128
	v_add_u32_e32 v5, 0xfffffe00, v128
	v_add_u32_e32 v6, 0x20000, v0
	v_lshrrev_b32_e32 v7, 8, v128
	s_mov_b64 s[0:1], 0
	s_waitcnt lgkmcnt(0)
	v_mov_b64_e32 v[0:1], s[2:3]
	s_mov_b64 s[4:5], 0x600
	s_mov_b32 s10, 0x2aaaaaab
	s_movk_i32 s11, 0x60
	v_mov_b32_e32 v9, 0x358637bd
	s_movk_i32 s12, 0x8ff
	v_mov_b32_e32 v10, 0xc0
	v_mov_b32_e32 v11, 0xc1
	v_and_b32_e32 v110, 0xff, v128
	s_lshr_b32 s98, s91, 2
	v_mov_b32_e32 v111, 0x358637bd
	s_mul_i32 s99, s98, s72
	s_add_i32 s99, s99, s2
	s_cmp_lt_u32 s99, 0x600
	s_cselect_b32 s99, s99, s2
	s_and_b32 s100, s99, 7
	s_mul_i32 s100, s100, 0xc0
	s_lshr_b32 s101, s99, 3
	s_add_i32 s100, s100, s101
	s_mul_hi_u32 s101, s100, 0x2aaaaab
	s_lshl_b32 s101, s101, 3
	s_and_b32 s100, s100, 7
	s_or_b32 s101, s101, s100
	s_lshl_b32 s101, s101, 8
	v_add_u32_e32 v108, s101, v110
	v_lshlrev_b32_e32 v108, 6, v108
	v_mov_b32_e32 v109, 0
	v_lshl_add_u64 v[108:109], s[18:19], 0, v[108:109]
	global_load_dwordx4 v[12:15], v[108:109], off
	global_load_dwordx4 v[16:19], v[108:109], off offset:16
	global_load_dwordx4 v[20:23], v[108:109], off offset:32
	global_load_dwordx4 v[24:27], v[108:109], off offset:48
	s_add_i32 s98, s98, 2
	s_mul_i32 s99, s98, s72
	s_add_i32 s99, s99, s2
	s_cmp_lt_u32 s99, 0x600
	s_cselect_b32 s99, s99, s2
	s_and_b32 s100, s99, 7
	s_mul_i32 s100, s100, 0xc0
	s_lshr_b32 s101, s99, 3
	s_add_i32 s100, s100, s101
	s_mul_hi_u32 s101, s100, 0x2aaaaab
	s_lshl_b32 s101, s101, 3
	s_and_b32 s100, s100, 7
	s_or_b32 s101, s101, s100
	s_lshl_b32 s101, s101, 8
	v_add_u32_e32 v108, s101, v110
	v_lshlrev_b32_e32 v108, 6, v108
	v_mov_b32_e32 v109, 0
	v_lshl_add_u64 v[108:109], s[18:19], 0, v[108:109]
	global_load_dwordx4 v[28:31], v[108:109], off
	global_load_dwordx4 v[32:35], v[108:109], off offset:16
	global_load_dwordx4 v[36:39], v[108:109], off offset:32
	global_load_dwordx4 v[40:43], v[108:109], off offset:48
	s_add_i32 s98, s98, 2
	s_mul_i32 s99, s98, s72
	s_add_i32 s99, s99, s2
	s_cmp_lt_u32 s99, 0x600
	s_cselect_b32 s99, s99, s2
	s_and_b32 s100, s99, 7
	s_mul_i32 s100, s100, 0xc0
	s_lshr_b32 s101, s99, 3
	s_add_i32 s100, s100, s101
	s_mul_hi_u32 s101, s100, 0x2aaaaab
	s_lshl_b32 s101, s101, 3
	s_and_b32 s100, s100, 7
	s_or_b32 s101, s101, s100
	s_lshl_b32 s101, s101, 8
	v_add_u32_e32 v108, s101, v110
	v_lshlrev_b32_e32 v108, 6, v108
	v_mov_b32_e32 v109, 0
	v_lshl_add_u64 v[108:109], s[18:19], 0, v[108:109]
	global_load_dwordx4 v[44:47], v[108:109], off
	global_load_dwordx4 v[48:51], v[108:109], off offset:16
	global_load_dwordx4 v[52:55], v[108:109], off offset:32
	global_load_dwordx4 v[56:59], v[108:109], off offset:48
	s_add_i32 s98, s98, 2
	v_lshlrev_b32_e32 v112, 2, v128
	v_add_u32_e32 v112, 0x20000, v112
	s_waitcnt vmcnt(8)
	v_pk_add_f32 v[114:115], v[14:15], v[18:19]
	v_pk_add_f32 v[116:117], v[12:13], v[16:17]
	v_pk_add_f32 v[118:119], v[22:23], v[26:27]
	v_pk_add_f32 v[120:121], v[20:21], v[24:25]
	v_pk_add_f32 v[114:115], v[114:115], v[118:119]
	v_pk_add_f32 v[116:117], v[116:117], v[120:121]
	v_add_f32_e32 v116, v117, v116
	v_add_f32_e32 v114, v114, v115
	v_add_f32_e32 v114, v116, v114
	v_fmamk_f32 v114, v114, 0x3a800000, v111
	v_rsq_f32_e32 v114, v114
	ds_write_b32 v112, v114
	s_waitcnt vmcnt(4)
	v_pk_add_f32 v[114:115], v[30:31], v[34:35]
	v_pk_add_f32 v[116:117], v[28:29], v[32:33]
	v_pk_add_f32 v[118:119], v[38:39], v[42:43]
	v_pk_add_f32 v[120:121], v[36:37], v[40:41]
	v_pk_add_f32 v[114:115], v[114:115], v[118:119]
	v_pk_add_f32 v[116:117], v[116:117], v[120:121]
	v_add_f32_e32 v116, v117, v116
	v_add_f32_e32 v114, v114, v115
	v_add_f32_e32 v114, v116, v114
	v_fmamk_f32 v114, v114, 0x3a800000, v111
	v_rsq_f32_e32 v114, v114
	ds_write_b32 v112, v114 offset:2048
	s_waitcnt vmcnt(0)
	v_pk_add_f32 v[114:115], v[46:47], v[50:51]
	v_pk_add_f32 v[116:117], v[44:45], v[48:49]
	v_pk_add_f32 v[118:119], v[54:55], v[58:59]
	v_pk_add_f32 v[120:121], v[52:53], v[56:57]
	v_pk_add_f32 v[114:115], v[114:115], v[118:119]
	v_pk_add_f32 v[116:117], v[116:117], v[120:121]
	v_add_f32_e32 v116, v117, v116
	v_add_f32_e32 v114, v114, v115
	v_add_f32_e32 v114, v116, v114
	v_fmamk_f32 v114, v114, 0x3a800000, v111
	v_rsq_f32_e32 v114, v114
	ds_write_b32 v112, v114 offset:4096

.LBB0_654:
	s_ashr_i32 s43, s42, 31
	s_lshl_b64 s[12:13], s[42:43], 19
	s_add_u32 s48, s14, s12
	s_addc_u32 s49, s15, s13
	s_and_b64 s[12:13], s[6:7], exec
	s_cselect_b32 s9, s49, s53
	s_cselect_b32 s10, s48, s52
	s_ashr_i32 s41, s40, 31
	s_lshl_b64 s[12:13], s[40:41], 19
	s_add_u32 s50, s63, s12
	s_addc_u32 s51, s64, s13
	s_and_b64 s[12:13], s[6:7], exec
	s_cselect_b32 s12, s51, s55
	s_cselect_b32 s13, s50, s54
	s_add_u32 s52, s52, 0x40080
	s_addc_u32 s53, s53, 0
	s_add_u32 s41, s54, 0x100
	s_addc_u32 s43, s55, 0
	s_mov_b32 s77, -2
	s_waitcnt lgkmcnt(0)
	s_setprio 0
	s_cmp_lg_u32 s93, 1
	s_cselect_b32 s100, s99, 0
	s_cmp_lg_u32 s100, 0
	s_cbranch_scc0 .Lmy_nobar2_7
	s_barrier

.LBB0_779:
	s_setprio 0
	s_cmp_lt_i32 s74, 9
	s_cselect_b64 s[0:1], -1, 0
	s_cmp_gt_i32 s75, 8
	s_cselect_b64 s[4:5], -1, 0
	s_and_b64 s[0:1], s[0:1], s[4:5]
	s_andn2_b64 vcc, exec, s[0:1]
	s_cbranch_vccnz .LBB0_948
	v_readlane_b32 s0, v238, 0
	s_cmpk_gt_i32 s0, 0xff
	v_readlane_b32 s1, v238, 1
	s_cbranch_scc1 .LBB0_894
	v_mbcnt_lo_u32_b32 v10, -1, 0
	s_add_u32 s3, s70, 0x1f900000
	v_lshrrev_b32_e32 v3, 3, v128
	v_mbcnt_hi_u32_b32 v10, -1, v10
	s_addc_u32 s64, s71, 0
	v_bfe_u32 v4, v128, 3, 6
	s_bfe_u32 s0, s76, 0x20006
	v_mov_b32_e32 v65, 0
	v_xor_b32_e32 v3, v3, v128
	v_and_b32_e32 v12, 64, v10
	s_mul_i32 s1, s0, 0x1200
	v_mul_u32_u24_e32 v2, 0xc00, v4
	s_waitcnt lgkmcnt(0)
	v_lshlrev_b32_e32 v66, 2, v128
	v_mov_b32_e32 v67, v65
	v_lshlrev_b32_e32 v4, 7, v4
	v_lshlrev_b32_e32 v3, 4, v3
	s_movk_i32 s10, 0x70
	s_lshl_b32 s0, s0, 4
	v_xor_b32_e32 v11, 16, v10
	v_add_u32_e32 v12, 64, v12
	v_lshl_add_u64 v[68:69], s[36:37], 0, v[66:67]
	v_lshl_add_u64 v[70:71], s[30:31], 0, v[66:67]
	v_and_or_b32 v67, v3, s10, v4
	v_med3_u32 v3, s0, 8, 40
	v_cmp_lt_i32_e32 vcc, v11, v12
	s_add_i32 s1, s1, 0
	v_readfirstlane_b32 s10, v3
	v_cndmask_b32_e32 v11, v10, v11, vcc
	v_lshrrev_b32_e32 v1, 4, v130
	s_add_i32 s12, s1, 0x21080
	s_movk_i32 s1, 0x1d1
	s_add_i32 s10, s10, -8
	v_lshlrev_b32_e32 v97, 2, v11
	v_xor_b32_e32 v11, 32, v10
	v_and_b32_e32 v7, 15, v128
	v_cmp_gt_u32_e64 s[4:5], s1, v128
	s_add_i32 s1, 0, 0x20f80
	v_lshlrev_b32_e32 v4, 3, v1
	v_mov_b32_e32 v5, v65
	v_cmp_lt_i32_e32 vcc, v11, v12
	s_and_b32 s65, s91, 4
	s_lshl_b32 s66, s10, 2
	s_and_b32 s67, s91, 0x3fffffc
	v_or_b32_e32 v95, s0, v7
	v_cndmask_b32_e32 v10, v10, v11, vcc
	s_cmp_eq_u32 s67, 4
	v_lshl_add_u64 v[74:75], s[20:21], 0, v[4:5]
	v_and_b32_e32 v5, 7, v128
	v_med3_u32 v3, v95, 8, 56
	v_lshl_add_u32 v96, v1, 5, s1
	v_lshlrev_b32_e32 v98, 2, v10
	v_lshl_add_u32 v10, v1, 2, s10
	s_cselect_b64 s[26:27], -1, 0
	s_cmpk_lt_u32 s76, 0x100
	v_add_lshl_u32 v103, s10, v7, 7
	v_bitop3_b32 v7, v1, v128, 7 bitop3:0x78
	v_bitop3_b32 v1, v1, v5, 4 bitop3:0x36
	v_add_u32_e32 v9, -8, v3
	v_add_u32_e32 v3, 8, v3
	s_cselect_b64 s[28:29], -1, 0
	s_add_i32 s0, 0, 0x20800
	v_lshlrev_b32_e32 v105, 4, v1
	v_sub_u32_e32 v1, v10, v95
	v_add_u32_e32 v94, s1, v66
	v_add_u32_e32 v102, s0, v66
	v_cmp_ge_u32_e32 vcc, v10, v9
	v_cmp_lt_u32_e64 s[0:1], v10, v3
	v_med3_i32 v106, v1, -15, 15
	v_or_b32_e32 v1, 1, v10
	s_and_b64 s[30:31], vcc, s[0:1]
	v_cmp_ge_u32_e32 vcc, v1, v9
	v_cmp_lt_u32_e64 s[0:1], v1, v3
	v_sub_u32_e32 v1, v1, v95
	v_med3_i32 v107, v1, -15, 15
	v_or_b32_e32 v1, 2, v10
	s_and_b64 s[36:37], vcc, s[0:1]
	v_cmp_ge_u32_e32 vcc, v1, v9
	v_cmp_lt_u32_e64 s[0:1], v1, v3
	v_sub_u32_e32 v1, v1, v95
	v_med3_i32 v108, v1, -15, 15
	v_or_b32_e32 v1, 3, v10
	s_and_b64 s[40:41], vcc, s[0:1]
	v_cmp_ge_u32_e32 vcc, v1, v9
	v_cmp_lt_u32_e64 s[0:1], v1, v3
	v_sub_u32_e32 v1, v1, v95
	v_med3_i32 v109, v1, -15, 15
	v_add_u32_e32 v1, 16, v10
	s_and_b64 s[42:43], vcc, s[0:1]
	v_cmp_ge_u32_e32 vcc, v1, v9
	v_cmp_lt_u32_e64 s[0:1], v1, v3
	v_sub_u32_e32 v1, v1, v95
	v_med3_i32 v110, v1, -15, 15
	v_add_u32_e32 v1, 17, v10
	s_and_b64 s[48:49], vcc, s[0:1]
	v_cmp_ge_u32_e32 vcc, v1, v9
	v_cmp_lt_u32_e64 s[0:1], v1, v3
	v_sub_u32_e32 v1, v1, v95
	v_med3_i32 v111, v1, -15, 15
	v_add_u32_e32 v1, 18, v10
	s_and_b64 s[50:51], vcc, s[0:1]
	v_cmp_ge_u32_e32 vcc, v1, v9
	v_cmp_lt_u32_e64 s[0:1], v1, v3
	v_sub_u32_e32 v1, v1, v95
	v_lshrrev_b32_e32 v6, 2, v128
	v_lshlrev_b32_e32 v8, 3, v128
	v_med3_i32 v112, v1, -15, 15
	v_add_u32_e32 v1, 19, v10
	v_and_b32_e32 v0, 56, v8
	v_and_or_b32 v6, v6, 3, v10
	v_and_b32_e32 v99, 8, v8
	v_bfe_u32 v8, v128, 1, 1
	s_and_b64 s[52:53], vcc, s[0:1]
	v_cmp_ge_u32_e32 vcc, v1, v9
	v_cmp_lt_u32_e64 s[0:1], v1, v3
	v_sub_u32_e32 v1, v1, v95
	v_med3_i32 v113, v1, -15, 15
	v_bitop3_b32 v1, v6, v8, 7 bitop3:0x6c
	v_lshlrev_b32_e32 v114, 4, v1
	v_or_b32_e32 v1, 2, v8
	v_bitop3_b32 v1, v6, v1, 7 bitop3:0x6c
	v_lshlrev_b32_e32 v115, 4, v1
	v_or_b32_e32 v1, 4, v8
	v_bitop3_b32 v1, v6, v1, 7 bitop3:0x6c
	v_and_b32_e32 v72, 48, v128
	v_lshlrev_b32_e32 v116, 4, v1
	v_or_b32_e32 v1, 6, v8
	v_mov_b32_e32 v73, v65
	v_lshlrev_b32_e32 v100, 7, v6
	v_lshlrev_b32_e32 v104, 4, v7
	v_bitop3_b32 v1, v6, v1, 7 bitop3:0x6c
	v_lshl_add_u64 v[6:7], s[70:71], 0, v[72:73]
	s_mov_b64 s[10:11], 0xf760000
	v_lshlrev_b32_e32 v11, 4, v130
	v_lshlrev_b32_e32 v12, 2, v130
	v_lshl_add_u64 v[76:77], v[6:7], 0, s[10:11]
	v_readlane_b32 s10, v238, 0
	s_mov_b32 s23, 0
	v_cmp_gt_u32_e64 s[6:7], 64, v128
	v_cmp_lt_u32_e64 s[8:9], 63, v128
	v_add_u32_e32 v101, 0x800, v100
	s_and_b64 s[0:1], vcc, s[0:1]
	v_lshlrev_b32_e32 v117, 4, v1
	v_lshlrev_b32_e32 v64, 1, v0
	v_lshlrev_b32_e32 v78, 1, v2
	s_mov_b64 s[54:55], 0x800
	v_lshlrev_b32_e32 v80, 2, v128
	v_mov_b32_e32 v73, 0x358637bd
	s_movk_i32 s77, 0x1800
	v_lshlrev_b32_e32 v82, 1, v4
	s_mov_b32 s79, 0x800000
	s_mov_b64 s[56:57], 0x60000
	v_add_u32_e32 v118, s12, v11
	v_add_u32_e32 v119, s12, v12
	s_mov_b32 s81, s10
	s_mov_b32 s82, s10
	v_readlane_b32 s11, v238, 1
	s_branch .LBB0_783

.LBB0_948:
	s_setprio 0
	s_cmp_lt_i32 s74, 10
	s_cselect_b64 s[0:1], -1, 0
	s_cmp_gt_i32 s75, 9
	s_cselect_b64 s[4:5], -1, 0
	s_and_b64 s[0:1], s[0:1], s[4:5]
	s_andn2_b64 vcc, exec, s[0:1]
	s_cbranch_vccnz .LBB0_1045
	s_cmpk_lt_i32 s2, 0x200
	s_cselect_b64 s[4:5], -1, 0
	s_cmpk_gt_i32 s2, 0x1ff
	v_readfirstlane_b32 s6, v128
	s_cbranch_scc0 .LBB0_952
	s_andn2_b64 vcc, exec, s[4:5]
	s_cbranch_vccz .LBB0_957

.LBB0_968:
	s_ashr_i32 s29, s28, 31
	s_lshl_b64 s[12:13], s[28:29], 19
	s_add_u32 s30, s20, s12
	s_addc_u32 s31, s21, s13
	s_and_b64 s[12:13], s[6:7], exec
	s_cselect_b32 s12, s31, s41
	s_cselect_b32 s13, s30, s40
	s_ashr_i32 s27, s26, 31
	s_lshl_b64 s[34:35], s[26:27], 19
	s_add_u32 s36, s3, s34
	s_addc_u32 s37, s50, s35
	s_and_b64 s[34:35], s[6:7], exec
	s_cselect_b32 s27, s37, s43
	s_cselect_b32 s29, s36, s42
	s_add_u32 s40, s40, 0x40080
	s_addc_u32 s41, s41, 0
	s_add_u32 s39, s42, 0x100
	s_addc_u32 s67, s43, 0
	s_mov_b32 s77, -2
	s_waitcnt lgkmcnt(0)
	s_setprio 0
	s_cmp_lg_u32 s66, 1
	s_cselect_b32 s100, s99, 0
	s_cmp_lg_u32 s100, 0
	s_cbranch_scc0 .Lmy_nobar2_9
	s_barrier

.LBB0_1045:
	s_setprio 0
	s_cmp_lt_i32 s74, 11
	s_cselect_b64 s[0:1], -1, 0
	s_cmp_gt_i32 s75, 10
	s_cselect_b64 s[4:5], -1, 0
	s_and_b64 s[0:1], s[0:1], s[4:5]
	s_andn2_b64 vcc, exec, s[0:1]
	s_cbranch_vccnz .LBB0_1120
	v_lshlrev_b32_e32 v8, 2, v128
	s_ashr_i32 s3, s2, 31
	s_waitcnt vmcnt(0)
	v_add_u32_e32 v0, 0, v8
	s_ashr_i32 s42, s72, 31
	s_mov_b32 s43, s72
	v_and_b32_e32 v4, 0xff, v128
	v_add_u32_e32 v5, 0xfffffe00, v128
	v_add_u32_e32 v6, 0x20000, v0
	v_lshrrev_b32_e32 v7, 8, v128
	s_mov_b64 s[0:1], 0
	s_waitcnt lgkmcnt(0)
	v_mov_b64_e32 v[0:1], s[2:3]
	s_mov_b64 s[4:5], 0xb00
	s_mov_b32 s10, 0x2e8ba2e9
	s_movk_i32 s11, 0xb0
	v_mov_b32_e32 v9, 0x358637bd
	s_movk_i32 s12, 0x8ff
	v_mov_b32_e32 v10, 0x160
	v_mov_b32_e32 v11, 0x161
	v_and_b32_e32 v110, 0xff, v128
	s_lshr_b32 s98, s91, 2
	v_mov_b32_e32 v111, 0x358637bd
	s_mul_i32 s99, s98, s72
	s_add_i32 s99, s99, s2
	s_cmp_lt_u32 s99, 0xb00
	s_cselect_b32 s99, s99, s2
	s_and_b32 s100, s99, 7
	s_mul_i32 s100, s100, 0x160
	s_lshr_b32 s101, s99, 3
	s_add_i32 s100, s100, s101
	s_mul_hi_u32 s101, s100, 0x1745d18
	s_lshl_b32 s101, s101, 3
	s_and_b32 s100, s100, 7
	s_or_b32 s101, s101, s100
	s_lshl_b32 s101, s101, 8
	v_add_u32_e32 v108, s101, v110
	v_lshlrev_b32_e32 v108, 6, v108
	v_mov_b32_e32 v109, 0
	v_lshl_add_u64 v[108:109], s[18:19], 0, v[108:109]
	global_load_dwordx4 v[12:15], v[108:109], off
	global_load_dwordx4 v[16:19], v[108:109], off offset:16
	global_load_dwordx4 v[20:23], v[108:109], off offset:32
	global_load_dwordx4 v[24:27], v[108:109], off offset:48
	s_add_i32 s98, s98, 2
	s_mul_i32 s99, s98, s72
	s_add_i32 s99, s99, s2
	s_cmp_lt_u32 s99, 0xb00
	s_cselect_b32 s99, s99, s2
	s_and_b32 s100, s99, 7
	s_mul_i32 s100, s100, 0x160
	s_lshr_b32 s101, s99, 3
	s_add_i32 s100, s100, s101
	s_mul_hi_u32 s101, s100, 0x1745d18
	s_lshl_b32 s101, s101, 3
	s_and_b32 s100, s100, 7
	s_or_b32 s101, s101, s100
	s_lshl_b32 s101, s101, 8
	v_add_u32_e32 v108, s101, v110
	v_lshlrev_b32_e32 v108, 6, v108
	v_mov_b32_e32 v109, 0
	v_lshl_add_u64 v[108:109], s[18:19], 0, v[108:109]
	global_load_dwordx4 v[28:31], v[108:109], off
	global_load_dwordx4 v[32:35], v[108:109], off offset:16
	global_load_dwordx4 v[36:39], v[108:109], off offset:32
	global_load_dwordx4 v[40:43], v[108:109], off offset:48
	s_add_i32 s98, s98, 2
	s_mul_i32 s99, s98, s72
	s_add_i32 s99, s99, s2
	s_cmp_lt_u32 s99, 0xb00
	s_cselect_b32 s99, s99, s2
	s_and_b32 s100, s99, 7
	s_mul_i32 s100, s100, 0x160
	s_lshr_b32 s101, s99, 3
	s_add_i32 s100, s100, s101
	s_mul_hi_u32 s101, s100, 0x1745d18
	s_lshl_b32 s101, s101, 3
	s_and_b32 s100, s100, 7
	s_or_b32 s101, s101, s100
	s_lshl_b32 s101, s101, 8
	v_add_u32_e32 v108, s101, v110
	v_lshlrev_b32_e32 v108, 6, v108
	v_mov_b32_e32 v109, 0
	v_lshl_add_u64 v[108:109], s[18:19], 0, v[108:109]
	global_load_dwordx4 v[44:47], v[108:109], off
	global_load_dwordx4 v[48:51], v[108:109], off offset:16
	global_load_dwordx4 v[52:55], v[108:109], off offset:32
	global_load_dwordx4 v[56:59], v[108:109], off offset:48
	s_add_i32 s98, s98, 2
	s_mul_i32 s99, s98, s72
	s_add_i32 s99, s99, s2
	s_cmp_lt_u32 s99, 0xb00
	s_cselect_b32 s99, s99, s2
	s_and_b32 s100, s99, 7
	s_mul_i32 s100, s100, 0x160
	s_lshr_b32 s101, s99, 3
	s_add_i32 s100, s100, s101
	s_mul_hi_u32 s101, s100, 0x1745d18
	s_lshl_b32 s101, s101, 3
	s_and_b32 s100, s100, 7
	s_or_b32 s101, s101, s100
	s_lshl_b32 s101, s101, 8
	v_add_u32_e32 v108, s101, v110
	v_lshlrev_b32_e32 v108, 6, v108
	v_mov_b32_e32 v109, 0
	v_lshl_add_u64 v[108:109], s[18:19], 0, v[108:109]
	global_load_dwordx4 v[60:63], v[108:109], off
	global_load_dwordx4 v[64:67], v[108:109], off offset:16
	global_load_dwordx4 v[68:71], v[108:109], off offset:32
	global_load_dwordx4 v[72:75], v[108:109], off offset:48
	s_add_i32 s98, s98, 2
	s_mul_i32 s99, s98, s72
	s_add_i32 s99, s99, s2
	s_cmp_lt_u32 s99, 0xb00
	s_cselect_b32 s99, s99, s2
	s_and_b32 s100, s99, 7
	s_mul_i32 s100, s100, 0x160
	s_lshr_b32 s101, s99, 3
	s_add_i32 s100, s100, s101
	s_mul_hi_u32 s101, s100, 0x1745d18
	s_lshl_b32 s101, s101, 3
	s_and_b32 s100, s100, 7
	s_or_b32 s101, s101, s100
	s_lshl_b32 s101, s101, 8
	v_add_u32_e32 v108, s101, v110
	v_lshlrev_b32_e32 v108, 6, v108
	v_mov_b32_e32 v109, 0
	v_lshl_add_u64 v[108:109], s[18:19], 0, v[108:109]
	global_load_dwordx4 v[76:79], v[108:109], off
	global_load_dwordx4 v[80:83], v[108:109], off offset:16
	global_load_dwordx4 v[84:87], v[108:109], off offset:32
	global_load_dwordx4 v[88:91], v[108:109], off offset:48
	s_add_i32 s98, s98, 2
	s_mul_i32 s99, s98, s72
	s_add_i32 s99, s99, s2
	s_cmp_lt_u32 s99, 0xb00
	s_cselect_b32 s99, s99, s2
	s_and_b32 s100, s99, 7
	s_mul_i32 s100, s100, 0x160
	s_lshr_b32 s101, s99, 3
	s_add_i32 s100, s100, s101
	s_mul_hi_u32 s101, s100, 0x1745d18
	s_lshl_b32 s101, s101, 3
	s_and_b32 s100, s100, 7
	s_or_b32 s101, s101, s100
	s_lshl_b32 s101, s101, 8
	v_add_u32_e32 v108, s101, v110
	v_lshlrev_b32_e32 v108, 6, v108
	v_mov_b32_e32 v109, 0
	v_lshl_add_u64 v[108:109], s[18:19], 0, v[108:109]
	global_load_dwordx4 v[92:95], v[108:109], off
	global_load_dwordx4 v[96:99], v[108:109], off offset:16
	global_load_dwordx4 v[100:103], v[108:109], off offset:32
	global_load_dwordx4 v[104:107], v[108:109], off offset:48
	s_add_i32 s98, s98, 2
	v_lshlrev_b32_e32 v112, 2, v128
	v_add_u32_e32 v112, 0x20000, v112
	s_waitcnt vmcnt(20)
	v_pk_add_f32 v[114:115], v[14:15], v[18:19]
	v_pk_add_f32 v[116:117], v[12:13], v[16:17]
	v_pk_add_f32 v[118:119], v[22:23], v[26:27]
	v_pk_add_f32 v[120:121], v[20:21], v[24:25]
	v_pk_add_f32 v[114:115], v[114:115], v[118:119]
	v_pk_add_f32 v[116:117], v[116:117], v[120:121]
	v_add_f32_e32 v116, v117, v116
	v_add_f32_e32 v114, v114, v115
	v_add_f32_e32 v114, v116, v114
	v_fmamk_f32 v114, v114, 0x3a800000, v111
	v_rsq_f32_e32 v114, v114
	ds_write_b32 v112, v114
	s_waitcnt vmcnt(16)
	v_pk_add_f32 v[114:115], v[30:31], v[34:35]
	v_pk_add_f32 v[116:117], v[28:29], v[32:33]
	v_pk_add_f32 v[118:119], v[38:39], v[42:43]
	v_pk_add_f32 v[120:121], v[36:37], v[40:41]
	v_pk_add_f32 v[114:115], v[114:115], v[118:119]
	v_pk_add_f32 v[116:117], v[116:117], v[120:121]
	v_add_f32_e32 v116, v117, v116
	v_add_f32_e32 v114, v114, v115
	v_add_f32_e32 v114, v116, v114
	v_fmamk_f32 v114, v114, 0x3a800000, v111
	v_rsq_f32_e32 v114, v114
	ds_write_b32 v112, v114 offset:2048
	s_waitcnt vmcnt(12)
	v_pk_add_f32 v[114:115], v[46:47], v[50:51]
	v_pk_add_f32 v[116:117], v[44:45], v[48:49]
	v_pk_add_f32 v[118:119], v[54:55], v[58:59]
	v_pk_add_f32 v[120:121], v[52:53], v[56:57]
	v_pk_add_f32 v[114:115], v[114:115], v[118:119]
	v_pk_add_f32 v[116:117], v[116:117], v[120:121]
	v_add_f32_e32 v116, v117, v116
	v_add_f32_e32 v114, v114, v115
	v_add_f32_e32 v114, v116, v114
	v_fmamk_f32 v114, v114, 0x3a800000, v111
	v_rsq_f32_e32 v114, v114
	ds_write_b32 v112, v114 offset:4096
	s_waitcnt vmcnt(8)
	v_pk_add_f32 v[114:115], v[62:63], v[66:67]
	v_pk_add_f32 v[116:117], v[60:61], v[64:65]
	v_pk_add_f32 v[118:119], v[70:71], v[74:75]
	v_pk_add_f32 v[120:121], v[68:69], v[72:73]
	v_pk_add_f32 v[114:115], v[114:115], v[118:119]
	v_pk_add_f32 v[116:117], v[116:117], v[120:121]
	v_add_f32_e32 v116, v117, v116
	v_add_f32_e32 v114, v114, v115
	v_add_f32_e32 v114, v116, v114
	v_fmamk_f32 v114, v114, 0x3a800000, v111
	v_rsq_f32_e32 v114, v114
	ds_write_b32 v112, v114 offset:6144
	s_waitcnt vmcnt(4)
	v_pk_add_f32 v[114:115], v[78:79], v[82:83]
	v_pk_add_f32 v[116:117], v[76:77], v[80:81]
	v_pk_add_f32 v[118:119], v[86:87], v[90:91]
	v_pk_add_f32 v[120:121], v[84:85], v[88:89]
	v_pk_add_f32 v[114:115], v[114:115], v[118:119]
	v_pk_add_f32 v[116:117], v[116:117], v[120:121]
	v_add_f32_e32 v116, v117, v116
	v_add_f32_e32 v114, v114, v115
	v_add_f32_e32 v114, v116, v114
	v_fmamk_f32 v114, v114, 0x3a800000, v111
	v_rsq_f32_e32 v114, v114
	ds_write_b32 v112, v114 offset:8192
	s_waitcnt vmcnt(0)
	v_pk_add_f32 v[114:115], v[94:95], v[98:99]
	v_pk_add_f32 v[116:117], v[92:93], v[96:97]
	v_pk_add_f32 v[118:119], v[102:103], v[106:107]
	v_pk_add_f32 v[120:121], v[100:101], v[104:105]
	v_pk_add_f32 v[114:115], v[114:115], v[118:119]
	v_pk_add_f32 v[116:117], v[116:117], v[120:121]
	v_add_f32_e32 v116, v117, v116
	v_add_f32_e32 v114, v114, v115
	v_add_f32_e32 v114, v116, v114
	v_fmamk_f32 v114, v114, 0x3a800000, v111
	v_rsq_f32_e32 v114, v114
	ds_write_b32 v112, v114 offset:10240

.LBB0_1058:
	s_ashr_i32 s23, s22, 31
	s_lshl_b64 s[26:27], s[22:23], 19
	s_add_u32 s26, s14, s26
	s_addc_u32 s27, s15, s27
	s_and_b64 s[28:29], s[4:5], exec
	s_cselect_b32 s23, s27, s37
	s_cselect_b32 s64, s26, s36
	s_ashr_i32 s11, s10, 31
	s_lshl_b64 s[28:29], s[10:11], 19
	s_add_u32 s28, s49, s28
	s_addc_u32 s29, s50, s29
	s_and_b64 s[34:35], s[4:5], exec
	s_cselect_b32 s11, s29, s39
	s_cselect_b32 s65, s28, s38
	s_add_u32 s36, s36, 0x40080
	s_addc_u32 s37, s37, 0
	s_add_u32 s66, s38, 0x100
	s_addc_u32 s67, s39, 0
	s_mov_b32 s77, -2
	s_setprio 0
	s_cmp_lg_u32 s62, 1
	s_cselect_b32 s100, s99, 0
	s_cmp_lg_u32 s100, 0
	s_cbranch_scc0 .Lmy_nobar2_10
	s_barrier

.LBB0_1120:
	s_setprio 0
	s_cmp_lt_i32 s74, 12
	s_cselect_b64 s[0:1], -1, 0
	s_cmp_gt_i32 s75, 11
	s_cselect_b64 s[4:5], -1, 0
	s_and_b64 s[0:1], s[0:1], s[4:5]
	s_andn2_b64 vcc, exec, s[0:1]
	s_cbranch_vccnz .LBB0_1221
	s_cmpk_lt_i32 s2, 0x200
	s_cselect_b64 s[0:1], -1, 0
	s_cmpk_gt_i32 s2, 0x1ff
	v_readfirstlane_b32 s6, v128
	s_cbranch_scc0 .LBB0_1124
	s_andn2_b64 vcc, exec, s[0:1]
	s_cbranch_vccz .LBB0_1129

.LBB0_1144:
	s_add_u32 s30, s30, 0xb0080
	s_addc_u32 s31, s31, 0
	s_add_u32 s13, s36, 0x100
	s_addc_u32 s63, s37, 0
	s_mov_b32 s64, -2
	s_waitcnt lgkmcnt(0)
	s_setprio 0
	s_cmp_lg_u32 s58, 1
	s_cselect_b32 s100, s99, 0
	s_cmp_lg_u32 s100, 0
	s_cbranch_scc0 .Lmy_nobar2_11
	s_barrier

.LBB0_1221:
	s_setprio 0
	s_cmp_lt_i32 s74, 13
	s_cselect_b64 s[0:1], -1, 0
	s_cmp_gt_i32 s75, 12
	s_cselect_b64 s[4:5], -1, 0
	s_and_b64 s[0:1], s[0:1], s[4:5]
	s_andn2_b64 vcc, exec, s[0:1]
	s_cbranch_vccnz .LBB0_1296
	v_lshlrev_b32_e32 v8, 2, v128
	s_ashr_i32 s3, s2, 31
	s_waitcnt vmcnt(0)
	v_add_u32_e32 v0, 0, v8
	s_ashr_i32 s42, s72, 31
	s_mov_b32 s43, s72
	v_and_b32_e32 v4, 0xff, v128
	v_add_u32_e32 v5, 0xfffffe00, v128
	v_add_u32_e32 v6, 0x20000, v0
	v_lshrrev_b32_e32 v7, 8, v128
	s_mov_b64 s[0:1], 0
	s_waitcnt lgkmcnt(0)
	v_mov_b64_e32 v[0:1], s[2:3]
	s_mov_b64 s[4:5], 0x600
	s_mov_b32 s10, 0x2aaaaaab
	s_movk_i32 s11, 0x60
	v_mov_b32_e32 v9, 0x358637bd
	s_movk_i32 s12, 0x8ff
	v_mov_b32_e32 v10, 0xc0
	v_mov_b32_e32 v11, 0xc1
	v_and_b32_e32 v110, 0xff, v128
	s_lshr_b32 s98, s91, 2
	v_mov_b32_e32 v111, 0x358637bd
	s_mul_i32 s99, s98, s72
	s_add_i32 s99, s99, s2
	s_cmp_lt_u32 s99, 0x600
	s_cselect_b32 s99, s99, s2
	s_and_b32 s100, s99, 7
	s_mul_i32 s100, s100, 0xc0
	s_lshr_b32 s101, s99, 3
	s_add_i32 s100, s100, s101
	s_mul_hi_u32 s101, s100, 0x2aaaaab
	s_lshl_b32 s101, s101, 3
	s_and_b32 s100, s100, 7
	s_or_b32 s101, s101, s100
	s_lshl_b32 s101, s101, 8
	v_add_u32_e32 v108, s101, v110
	v_lshlrev_b32_e32 v108, 6, v108
	v_mov_b32_e32 v109, 0
	v_lshl_add_u64 v[108:109], s[18:19], 0, v[108:109]
	global_load_dwordx4 v[12:15], v[108:109], off
	global_load_dwordx4 v[16:19], v[108:109], off offset:16
	global_load_dwordx4 v[20:23], v[108:109], off offset:32
	global_load_dwordx4 v[24:27], v[108:109], off offset:48
	s_add_i32 s98, s98, 2
	s_mul_i32 s99, s98, s72
	s_add_i32 s99, s99, s2
	s_cmp_lt_u32 s99, 0x600
	s_cselect_b32 s99, s99, s2
	s_and_b32 s100, s99, 7
	s_mul_i32 s100, s100, 0xc0
	s_lshr_b32 s101, s99, 3
	s_add_i32 s100, s100, s101
	s_mul_hi_u32 s101, s100, 0x2aaaaab
	s_lshl_b32 s101, s101, 3
	s_and_b32 s100, s100, 7
	s_or_b32 s101, s101, s100
	s_lshl_b32 s101, s101, 8
	v_add_u32_e32 v108, s101, v110
	v_lshlrev_b32_e32 v108, 6, v108
	v_mov_b32_e32 v109, 0
	v_lshl_add_u64 v[108:109], s[18:19], 0, v[108:109]
	global_load_dwordx4 v[28:31], v[108:109], off
	global_load_dwordx4 v[32:35], v[108:109], off offset:16
	global_load_dwordx4 v[36:39], v[108:109], off offset:32
	global_load_dwordx4 v[40:43], v[108:109], off offset:48
	s_add_i32 s98, s98, 2
	s_mul_i32 s99, s98, s72
	s_add_i32 s99, s99, s2
	s_cmp_lt_u32 s99, 0x600
	s_cselect_b32 s99, s99, s2
	s_and_b32 s100, s99, 7
	s_mul_i32 s100, s100, 0xc0
	s_lshr_b32 s101, s99, 3
	s_add_i32 s100, s100, s101
	s_mul_hi_u32 s101, s100, 0x2aaaaab
	s_lshl_b32 s101, s101, 3
	s_and_b32 s100, s100, 7
	s_or_b32 s101, s101, s100
	s_lshl_b32 s101, s101, 8
	v_add_u32_e32 v108, s101, v110
	v_lshlrev_b32_e32 v108, 6, v108
	v_mov_b32_e32 v109, 0
	v_lshl_add_u64 v[108:109], s[18:19], 0, v[108:109]
	global_load_dwordx4 v[44:47], v[108:109], off
	global_load_dwordx4 v[48:51], v[108:109], off offset:16
	global_load_dwordx4 v[52:55], v[108:109], off offset:32
	global_load_dwordx4 v[56:59], v[108:109], off offset:48
	s_add_i32 s98, s98, 2
	v_lshlrev_b32_e32 v112, 2, v128
	v_add_u32_e32 v112, 0x20000, v112
	s_waitcnt vmcnt(8)
	v_pk_add_f32 v[114:115], v[14:15], v[18:19]
	v_pk_add_f32 v[116:117], v[12:13], v[16:17]
	v_pk_add_f32 v[118:119], v[22:23], v[26:27]
	v_pk_add_f32 v[120:121], v[20:21], v[24:25]
	v_pk_add_f32 v[114:115], v[114:115], v[118:119]
	v_pk_add_f32 v[116:117], v[116:117], v[120:121]
	v_add_f32_e32 v116, v117, v116
	v_add_f32_e32 v114, v114, v115
	v_add_f32_e32 v114, v116, v114
	v_fmamk_f32 v114, v114, 0x3a800000, v111
	v_rsq_f32_e32 v114, v114
	ds_write_b32 v112, v114
	s_waitcnt vmcnt(4)
	v_pk_add_f32 v[114:115], v[30:31], v[34:35]
	v_pk_add_f32 v[116:117], v[28:29], v[32:33]
	v_pk_add_f32 v[118:119], v[38:39], v[42:43]
	v_pk_add_f32 v[120:121], v[36:37], v[40:41]
	v_pk_add_f32 v[114:115], v[114:115], v[118:119]
	v_pk_add_f32 v[116:117], v[116:117], v[120:121]
	v_add_f32_e32 v116, v117, v116
	v_add_f32_e32 v114, v114, v115
	v_add_f32_e32 v114, v116, v114
	v_fmamk_f32 v114, v114, 0x3a800000, v111
	v_rsq_f32_e32 v114, v114
	ds_write_b32 v112, v114 offset:2048
	s_waitcnt vmcnt(0)
	v_pk_add_f32 v[114:115], v[46:47], v[50:51]
	v_pk_add_f32 v[116:117], v[44:45], v[48:49]
	v_pk_add_f32 v[118:119], v[54:55], v[58:59]
	v_pk_add_f32 v[120:121], v[52:53], v[56:57]
	v_pk_add_f32 v[114:115], v[114:115], v[118:119]
	v_pk_add_f32 v[116:117], v[116:117], v[120:121]
	v_add_f32_e32 v116, v117, v116
	v_add_f32_e32 v114, v114, v115
	v_add_f32_e32 v114, v116, v114
	v_fmamk_f32 v114, v114, 0x3a800000, v111
	v_rsq_f32_e32 v114, v114
	ds_write_b32 v112, v114 offset:4096

.LBB0_1234:
	s_ashr_i32 s23, s22, 31
	s_lshl_b64 s[26:27], s[22:23], 19
	s_add_u32 s26, s14, s26
	s_addc_u32 s27, s15, s27
	s_and_b64 s[28:29], s[4:5], exec
	s_cselect_b32 s23, s27, s37
	s_cselect_b32 s64, s26, s36
	s_ashr_i32 s11, s10, 31
	s_lshl_b64 s[28:29], s[10:11], 19
	s_add_u32 s28, s49, s28
	s_addc_u32 s29, s50, s29
	s_and_b64 s[34:35], s[4:5], exec
	s_cselect_b32 s11, s29, s39
	s_cselect_b32 s65, s28, s38
	s_add_u32 s36, s36, 0x40080
	s_addc_u32 s37, s37, 0
	s_add_u32 s66, s38, 0x100
	s_addc_u32 s67, s39, 0
	s_mov_b32 s77, -2
	s_setprio 0
	s_cmp_lg_u32 s58, 1
	s_cselect_b32 s100, s99, 0
	s_cmp_lg_u32 s100, 0
	s_cbranch_scc0 .Lmy_nobar2_12
	s_barrier

.LBB0_1296:
	s_add_u32 s8, s70, 0x1b900000
	s_addc_u32 s9, s71, 0
	s_setprio 0
	s_cmp_lt_i32 s74, 14
	s_cselect_b64 s[0:1], -1, 0
	s_cmp_gt_i32 s75, 13
	s_cselect_b64 s[4:5], -1, 0
	s_and_b64 s[0:1], s[0:1], s[4:5]
	s_andn2_b64 vcc, exec, s[0:1]
	s_cbranch_vccnz .LBB0_1400
	s_cmpk_lt_i32 s80, 0x4000
	s_cselect_b64 s[4:5], -1, 0
	s_cmpk_gt_i32 s80, 0x3fff
	s_cbranch_scc1 .LBB0_1303
	s_lshl_b32 s0, s80, 1
	s_and_b32 s6, s0, 0x7c0
	s_and_b32 s3, s0, 0xfffff800
	s_lshl_b32 s0, s80, 7
	s_add_i32 s6, s6, -1
	s_and_b32 s0, s0, 0xf80
	s_add_u32 s0, s16, s0
	s_waitcnt vmcnt(0)
	v_lshlrev_b32_e32 v0, 4, v128
	s_addc_u32 s1, s17, 0
	s_waitcnt lgkmcnt(1)
	v_and_b32_e32 v34, 0x70, v0
	v_mov_b32_e32 v35, 0
	v_lshrrev_b32_e32 v32, 3, v130
	v_lshl_add_u64 v[38:39], s[0:1], 0, v[34:35]
	v_mov_b32_e32 v34, v35
	v_add_u32_e32 v4, s6, v32
	s_movk_i32 s7, 0x800
	v_mov_b32_e32 v36, v35
	v_mov_b32_e32 v37, v35
	s_waitcnt lgkmcnt(0)
	v_mov_b64_e32 v[0:1], v[34:35]
	v_cmp_gt_u32_e32 vcc, s7, v4
	v_mov_b64_e32 v[2:3], v[36:37]
	s_and_saveexec_b64 s[0:1], vcc
	s_cbranch_execz .LBB0_1300
	v_or_b32_e32 v0, s3, v4
	s_movk_i32 s10, 0x1800
	v_mad_i64_i32 v[0:1], s[10:11], v0, s10, v[38:39]
	global_load_dwordx4 v[0:3], v[0:1], off

.LBB0_1400:
	s_setprio 0
	s_cmp_lt_i32 s74, 15
	s_cselect_b64 s[0:1], -1, 0
	s_cmp_gt_i32 s75, 14
	s_cselect_b64 s[4:5], -1, 0
	s_and_b64 s[0:1], s[0:1], s[4:5]
	s_andn2_b64 vcc, exec, s[0:1]
	s_cbranch_vccnz .LBB0_1474
	v_readlane_b32 s0, v238, 0
	s_cmpk_gt_i32 s0, 0x3ff
	v_readlane_b32 s1, v238, 1
	s_cbranch_scc1 .LBB0_1420
	s_add_u32 s0, s70, 0x6600000
	v_readlane_b32 s4, v238, 0
	s_addc_u32 s1, s71, 0
	v_readlane_b32 s5, v238, 1
	s_mov_b32 s6, s4
	s_ashr_i32 s7, s4, 31
	s_lshl_b64 s[4:5], s[6:7], 16
	s_add_u32 s4, s8, s4
	s_addc_u32 s5, s9, s5
	v_mov_b32_e32 v113, 0
	v_lshlrev_b32_e32 v112, 4, v128
	s_waitcnt vmcnt(0)
	v_lshl_add_u64 v[12:13], s[4:5], 0, v[112:113]
	v_add_co_u32_e32 v8, vcc, 0x2000, v12
	s_mul_hi_i32 s3, s6, 0x2020
	s_nop 0
	v_addc_co_u32_e32 v9, vcc, 0, v13, vcc
	v_add_co_u32_e32 v10, vcc, 0x4000, v12
	s_mov_b32 s7, 0
	s_nop 0
	v_addc_co_u32_e32 v11, vcc, 0, v13, vcc
	v_add_co_u32_e32 v14, vcc, 0x6000, v12
	global_load_dwordx4 v[4:7], v[8:9], off
	s_waitcnt lgkmcnt(0)
	global_load_dwordx4 v[0:3], v[10:11], off
	v_addc_co_u32_e32 v15, vcc, 0, v13, vcc
	v_add_co_u32_e32 v20, vcc, 0x8000, v12
	s_movk_i32 s26, 0x6000
	s_nop 0
	v_addc_co_u32_e32 v21, vcc, 0, v13, vcc
	global_load_dwordx4 v[8:11], v[14:15], off
	global_load_dwordx4 v[16:19], v[20:21], off
	v_add_co_u32_e32 v14, vcc, 0xa000, v12
	s_mov_b32 s27, 0xa000
	s_nop 0
	v_addc_co_u32_e32 v15, vcc, 0, v13, vcc
	v_add_co_u32_e32 v28, vcc, 0xc000, v12
	v_mov_b32_e32 v36, v113
	s_nop 0
	v_addc_co_u32_e32 v29, vcc, 0, v13, vcc
	v_add_co_u32_e32 v32, vcc, 0xe000, v12
	global_load_dwordx4 v[20:23], v[14:15], off
	global_load_dwordx4 v[24:27], v[28:29], off
	v_addc_co_u32_e32 v33, vcc, 0, v13, vcc
	global_load_dwordx4 v[12:15], v112, s[4:5]
	global_load_dwordx4 v[28:31], v[32:33], off
	s_mov_b32 s4, s6
	v_writelane_b32 v238, s4, 0
	v_mov_b32_e32 v37, v113
	v_mov_b32_e32 v38, v113
	v_writelane_b32 v238, s5, 1
	s_mul_i32 s4, s6, 0x2020
	s_add_u32 s22, s0, s4
	s_addc_u32 s23, s1, s3
	global_load_dwordx4 v[32:35], v112, s[22:23]
	s_movk_i32 s3, 0x2000
	v_cmp_gt_u32_e64 s[4:5], 2, v128
	v_mov_b32_e32 v39, v113
	s_and_saveexec_b64 s[10:11], s[4:5]
	s_cbranch_execz .LBB0_1404
	v_lshl_add_u64 v[36:37], s[22:23], 0, v[112:113]
	v_add_co_u32_e32 v36, vcc, 0x2000, v36
	s_nop 1
	v_addc_co_u32_e32 v37, vcc, 0, v37, vcc
	global_load_dwordx4 v[36:39], v[36:37], off

.LBB0_1474:
	s_setprio 0
	s_cmp_lt_i32 s74, 16
	s_cselect_b64 s[0:1], -1, 0
	s_cmp_gt_i32 s75, 15
	s_cselect_b64 s[4:5], -1, 0
	s_and_b64 s[0:1], s[0:1], s[4:5]
	s_andn2_b64 vcc, exec, s[0:1]
	s_cbranch_vccnz .LBB0_1536
	s_cmpk_gt_i32 s80, 0x1fff
	s_cbranch_scc1 .LBB0_1482
	s_lshl_b32 s0, s91, 14
	s_add_i32 s0, s0, 0
	s_waitcnt vmcnt(0)
	v_lshlrev_b32_e32 v0, 4, v128
	v_lshrrev_b32_e32 v8, 3, v130
	v_and_b32_e32 v0, 0x70, v0
	s_waitcnt lgkmcnt(0)
	v_mov_b32_e32 v1, 0
	s_movk_i32 s3, 0x84
	v_mov_b32_e32 v4, s0
	v_lshl_add_u64 v[2:3], s[8:9], 0, v[0:1]
	v_add_u32_e32 v0, s0, v0
	v_mad_u32_u24 v9, v130, s3, v4
	v_mul_u32_u24_e32 v4, 0x84, v8
	s_mov_b32 s1, 0
	s_lshl_b32 s3, s80, 6
	s_lshl_b32 s8, s72, 9
	s_lshl_b32 s9, s80, 2
	s_lshl_b32 s10, s72, 5
	s_movk_i32 s11, 0x5000
	s_mov_b32 s22, 0x8000
	s_movk_i32 s23, 0x1000
	s_movk_i32 s26, 0x3000
	s_movk_i32 s27, 0x4000
	s_movk_i32 s28, 0x6000
	s_movk_i32 s29, 0x7000
	s_mov_b32 s30, 0x9000
	s_mov_b32 s31, 0xa000
	s_mov_b32 s36, 0xc000
	s_mov_b32 s37, 0xd000
	s_mov_b32 s38, 0xf000
	s_mov_b32 s39, 0x10000
	s_mov_b32 s40, 0x12000
	s_mov_b32 s41, 0x13000
	s_mov_b32 s42, 0x15000
	s_mov_b32 s43, 0x16000
	s_mov_b32 s48, 0x18000
	s_mov_b32 s49, 0x19000
	s_mov_b32 s50, 0x1b000
	s_mov_b32 s51, 0x1c000
	s_mov_b32 s52, 0x1e000
	s_mov_b32 s53, 0x1f000
	v_add_u32_e32 v10, v0, v4
	v_lshlrev_b32_e32 v4, 1, v130
	s_movk_i32 s54, 0x2000
	s_mov_b32 s55, 0xb000
	s_mov_b32 s56, 0xe000
	s_mov_b32 s57, 0x11000
	s_mov_b32 s58, 0x14000
	s_mov_b32 s59, 0x17000
	s_mov_b32 s60, 0x1a000
	s_mov_b32 s61, 0x1d000
	s_branch .LBB0_1478

.LBB0_1536:
	s_setprio 0
	s_cmp_lt_i32 s74, 17
	s_cselect_b64 s[0:1], -1, 0
	s_cmp_gt_i32 s75, 16
	s_cselect_b64 s[4:5], -1, 0
	s_and_b64 s[0:1], s[0:1], s[4:5]
	s_andn2_b64 vcc, exec, s[0:1]
	s_cbranch_vccnz .LBB0_1633
	s_cmpk_lt_i32 s2, 0x200
	s_cselect_b64 s[4:5], -1, 0
	s_cmpk_gt_i32 s2, 0x1ff
	v_readfirstlane_b32 s6, v128
	s_cbranch_scc0 .LBB0_1540
	s_andn2_b64 vcc, exec, s[4:5]
	s_cbranch_vccz .LBB0_1545

.LBB0_1556:
	s_ashr_i32 s29, s28, 31
	s_lshl_b64 s[12:13], s[28:29], 19
	s_add_u32 s30, s20, s12
	s_addc_u32 s31, s21, s13
	s_and_b64 s[12:13], s[6:7], exec
	s_cselect_b32 s12, s31, s41
	s_cselect_b32 s13, s30, s40
	s_ashr_i32 s27, s26, 31
	s_lshl_b64 s[34:35], s[26:27], 19
	s_add_u32 s36, s3, s34
	s_addc_u32 s37, s46, s35
	s_and_b64 s[34:35], s[6:7], exec
	s_cselect_b32 s27, s37, s43
	s_cselect_b32 s29, s36, s42
	s_add_u32 s40, s40, 0x40080
	s_addc_u32 s41, s41, 0
	s_add_u32 s39, s42, 0x100
	s_addc_u32 s61, s43, 0
	s_mov_b32 s62, -2
	s_waitcnt lgkmcnt(0)
	s_setprio 0
	s_cmp_lg_u32 s60, 1
	s_cselect_b32 s100, s99, 0
	s_cmp_lg_u32 s100, 0
	s_cbranch_scc0 .Lmy_nobar2_16
	s_barrier

.LBB0_1633:
	s_setprio 0
	s_cmp_lt_i32 s74, 18
	s_cselect_b64 s[0:1], -1, 0
	s_cmp_gt_i32 s75, 17
	s_cselect_b64 s[4:5], -1, 0
	s_and_b64 s[0:1], s[0:1], s[4:5]
	s_andn2_b64 vcc, exec, s[0:1]
	s_cbranch_vccnz .LBB0_1708
	s_waitcnt vmcnt(0)
	v_lshlrev_b32_e32 v8, 2, v128
	s_ashr_i32 s3, s2, 31
	v_add_u32_e32 v0, 0, v8
	s_ashr_i32 s42, s72, 31
	s_mov_b32 s43, s72
	v_and_b32_e32 v4, 0xff, v128
	v_add_u32_e32 v5, 0xfffffe00, v128
	v_add_u32_e32 v6, 0x20000, v0
	v_lshrrev_b32_e32 v7, 8, v128
	s_mov_b64 s[0:1], 0
	s_waitcnt lgkmcnt(0)
	v_mov_b64_e32 v[0:1], s[2:3]
	s_mov_b64 s[4:5], 0xb00
	s_mov_b32 s10, 0x2e8ba2e9
	s_movk_i32 s11, 0xb0
	v_mov_b32_e32 v9, 0x358637bd
	s_movk_i32 s12, 0x8ff
	v_mov_b32_e32 v10, 0x160
	v_mov_b32_e32 v11, 0x161
	v_and_b32_e32 v110, 0xff, v128
	s_lshr_b32 s98, s91, 2
	v_mov_b32_e32 v111, 0x358637bd
	s_mul_i32 s99, s98, s72
	s_add_i32 s99, s99, s2
	s_cmp_lt_u32 s99, 0xb00
	s_cselect_b32 s99, s99, s2
	s_and_b32 s100, s99, 7
	s_mul_i32 s100, s100, 0x160
	s_lshr_b32 s101, s99, 3
	s_add_i32 s100, s100, s101
	s_mul_hi_u32 s101, s100, 0x1745d18
	s_lshl_b32 s101, s101, 3
	s_and_b32 s100, s100, 7
	s_or_b32 s101, s101, s100
	s_lshl_b32 s101, s101, 8
	v_add_u32_e32 v108, s101, v110
	v_lshlrev_b32_e32 v108, 6, v108
	v_mov_b32_e32 v109, 0
	v_lshl_add_u64 v[108:109], s[18:19], 0, v[108:109]
	global_load_dwordx4 v[12:15], v[108:109], off
	global_load_dwordx4 v[16:19], v[108:109], off offset:16
	global_load_dwordx4 v[20:23], v[108:109], off offset:32
	global_load_dwordx4 v[24:27], v[108:109], off offset:48
	s_add_i32 s98, s98, 2
	s_mul_i32 s99, s98, s72
	s_add_i32 s99, s99, s2
	s_cmp_lt_u32 s99, 0xb00
	s_cselect_b32 s99, s99, s2
	s_and_b32 s100, s99, 7
	s_mul_i32 s100, s100, 0x160
	s_lshr_b32 s101, s99, 3
	s_add_i32 s100, s100, s101
	s_mul_hi_u32 s101, s100, 0x1745d18
	s_lshl_b32 s101, s101, 3
	s_and_b32 s100, s100, 7
	s_or_b32 s101, s101, s100
	s_lshl_b32 s101, s101, 8
	v_add_u32_e32 v108, s101, v110
	v_lshlrev_b32_e32 v108, 6, v108
	v_mov_b32_e32 v109, 0
	v_lshl_add_u64 v[108:109], s[18:19], 0, v[108:109]
	global_load_dwordx4 v[28:31], v[108:109], off
	global_load_dwordx4 v[32:35], v[108:109], off offset:16
	global_load_dwordx4 v[36:39], v[108:109], off offset:32
	global_load_dwordx4 v[40:43], v[108:109], off offset:48
	s_add_i32 s98, s98, 2
	s_mul_i32 s99, s98, s72
	s_add_i32 s99, s99, s2
	s_cmp_lt_u32 s99, 0xb00
	s_cselect_b32 s99, s99, s2
	s_and_b32 s100, s99, 7
	s_mul_i32 s100, s100, 0x160
	s_lshr_b32 s101, s99, 3
	s_add_i32 s100, s100, s101
	s_mul_hi_u32 s101, s100, 0x1745d18
	s_lshl_b32 s101, s101, 3
	s_and_b32 s100, s100, 7
	s_or_b32 s101, s101, s100
	s_lshl_b32 s101, s101, 8
	v_add_u32_e32 v108, s101, v110
	v_lshlrev_b32_e32 v108, 6, v108
	v_mov_b32_e32 v109, 0
	v_lshl_add_u64 v[108:109], s[18:19], 0, v[108:109]
	global_load_dwordx4 v[44:47], v[108:109], off
	global_load_dwordx4 v[48:51], v[108:109], off offset:16
	global_load_dwordx4 v[52:55], v[108:109], off offset:32
	global_load_dwordx4 v[56:59], v[108:109], off offset:48
	s_add_i32 s98, s98, 2
	s_mul_i32 s99, s98, s72
	s_add_i32 s99, s99, s2
	s_cmp_lt_u32 s99, 0xb00
	s_cselect_b32 s99, s99, s2
	s_and_b32 s100, s99, 7
	s_mul_i32 s100, s100, 0x160
	s_lshr_b32 s101, s99, 3
	s_add_i32 s100, s100, s101
	s_mul_hi_u32 s101, s100, 0x1745d18
	s_lshl_b32 s101, s101, 3
	s_and_b32 s100, s100, 7
	s_or_b32 s101, s101, s100
	s_lshl_b32 s101, s101, 8
	v_add_u32_e32 v108, s101, v110
	v_lshlrev_b32_e32 v108, 6, v108
	v_mov_b32_e32 v109, 0
	v_lshl_add_u64 v[108:109], s[18:19], 0, v[108:109]
	global_load_dwordx4 v[60:63], v[108:109], off
	global_load_dwordx4 v[64:67], v[108:109], off offset:16
	global_load_dwordx4 v[68:71], v[108:109], off offset:32
	global_load_dwordx4 v[72:75], v[108:109], off offset:48
	s_add_i32 s98, s98, 2
	s_mul_i32 s99, s98, s72
	s_add_i32 s99, s99, s2
	s_cmp_lt_u32 s99, 0xb00
	s_cselect_b32 s99, s99, s2
	s_and_b32 s100, s99, 7
	s_mul_i32 s100, s100, 0x160
	s_lshr_b32 s101, s99, 3
	s_add_i32 s100, s100, s101
	s_mul_hi_u32 s101, s100, 0x1745d18
	s_lshl_b32 s101, s101, 3
	s_and_b32 s100, s100, 7
	s_or_b32 s101, s101, s100
	s_lshl_b32 s101, s101, 8
	v_add_u32_e32 v108, s101, v110
	v_lshlrev_b32_e32 v108, 6, v108
	v_mov_b32_e32 v109, 0
	v_lshl_add_u64 v[108:109], s[18:19], 0, v[108:109]
	global_load_dwordx4 v[76:79], v[108:109], off
	global_load_dwordx4 v[80:83], v[108:109], off offset:16
	global_load_dwordx4 v[84:87], v[108:109], off offset:32
	global_load_dwordx4 v[88:91], v[108:109], off offset:48
	s_add_i32 s98, s98, 2
	s_mul_i32 s99, s98, s72
	s_add_i32 s99, s99, s2
	s_cmp_lt_u32 s99, 0xb00
	s_cselect_b32 s99, s99, s2
	s_and_b32 s100, s99, 7
	s_mul_i32 s100, s100, 0x160
	s_lshr_b32 s101, s99, 3
	s_add_i32 s100, s100, s101
	s_mul_hi_u32 s101, s100, 0x1745d18
	s_lshl_b32 s101, s101, 3
	s_and_b32 s100, s100, 7
	s_or_b32 s101, s101, s100
	s_lshl_b32 s101, s101, 8
	v_add_u32_e32 v108, s101, v110
	v_lshlrev_b32_e32 v108, 6, v108
	v_mov_b32_e32 v109, 0
	v_lshl_add_u64 v[108:109], s[18:19], 0, v[108:109]
	global_load_dwordx4 v[92:95], v[108:109], off
	global_load_dwordx4 v[96:99], v[108:109], off offset:16
	global_load_dwordx4 v[100:103], v[108:109], off offset:32
	global_load_dwordx4 v[104:107], v[108:109], off offset:48
	s_add_i32 s98, s98, 2
	v_lshlrev_b32_e32 v112, 2, v128
	v_add_u32_e32 v112, 0x20000, v112
	s_waitcnt vmcnt(20)
	v_pk_add_f32 v[114:115], v[14:15], v[18:19]
	v_pk_add_f32 v[116:117], v[12:13], v[16:17]
	v_pk_add_f32 v[118:119], v[22:23], v[26:27]
	v_pk_add_f32 v[120:121], v[20:21], v[24:25]
	v_pk_add_f32 v[114:115], v[114:115], v[118:119]
	v_pk_add_f32 v[116:117], v[116:117], v[120:121]
	v_add_f32_e32 v116, v117, v116
	v_add_f32_e32 v114, v114, v115
	v_add_f32_e32 v114, v116, v114
	v_fmamk_f32 v114, v114, 0x3a800000, v111
	v_rsq_f32_e32 v114, v114
	ds_write_b32 v112, v114
	s_waitcnt vmcnt(16)
	v_pk_add_f32 v[114:115], v[30:31], v[34:35]
	v_pk_add_f32 v[116:117], v[28:29], v[32:33]
	v_pk_add_f32 v[118:119], v[38:39], v[42:43]
	v_pk_add_f32 v[120:121], v[36:37], v[40:41]
	v_pk_add_f32 v[114:115], v[114:115], v[118:119]
	v_pk_add_f32 v[116:117], v[116:117], v[120:121]
	v_add_f32_e32 v116, v117, v116
	v_add_f32_e32 v114, v114, v115
	v_add_f32_e32 v114, v116, v114
	v_fmamk_f32 v114, v114, 0x3a800000, v111
	v_rsq_f32_e32 v114, v114
	ds_write_b32 v112, v114 offset:2048
	s_waitcnt vmcnt(12)
	v_pk_add_f32 v[114:115], v[46:47], v[50:51]
	v_pk_add_f32 v[116:117], v[44:45], v[48:49]
	v_pk_add_f32 v[118:119], v[54:55], v[58:59]
	v_pk_add_f32 v[120:121], v[52:53], v[56:57]
	v_pk_add_f32 v[114:115], v[114:115], v[118:119]
	v_pk_add_f32 v[116:117], v[116:117], v[120:121]
	v_add_f32_e32 v116, v117, v116
	v_add_f32_e32 v114, v114, v115
	v_add_f32_e32 v114, v116, v114
	v_fmamk_f32 v114, v114, 0x3a800000, v111
	v_rsq_f32_e32 v114, v114
	ds_write_b32 v112, v114 offset:4096
	s_waitcnt vmcnt(8)
	v_pk_add_f32 v[114:115], v[62:63], v[66:67]
	v_pk_add_f32 v[116:117], v[60:61], v[64:65]
	v_pk_add_f32 v[118:119], v[70:71], v[74:75]
	v_pk_add_f32 v[120:121], v[68:69], v[72:73]
	v_pk_add_f32 v[114:115], v[114:115], v[118:119]
	v_pk_add_f32 v[116:117], v[116:117], v[120:121]
	v_add_f32_e32 v116, v117, v116
	v_add_f32_e32 v114, v114, v115
	v_add_f32_e32 v114, v116, v114
	v_fmamk_f32 v114, v114, 0x3a800000, v111
	v_rsq_f32_e32 v114, v114
	ds_write_b32 v112, v114 offset:6144
	s_waitcnt vmcnt(4)
	v_pk_add_f32 v[114:115], v[78:79], v[82:83]
	v_pk_add_f32 v[116:117], v[76:77], v[80:81]
	v_pk_add_f32 v[118:119], v[86:87], v[90:91]
	v_pk_add_f32 v[120:121], v[84:85], v[88:89]
	v_pk_add_f32 v[114:115], v[114:115], v[118:119]
	v_pk_add_f32 v[116:117], v[116:117], v[120:121]
	v_add_f32_e32 v116, v117, v116
	v_add_f32_e32 v114, v114, v115
	v_add_f32_e32 v114, v116, v114
	v_fmamk_f32 v114, v114, 0x3a800000, v111
	v_rsq_f32_e32 v114, v114
	ds_write_b32 v112, v114 offset:8192
	s_waitcnt vmcnt(0)
	v_pk_add_f32 v[114:115], v[94:95], v[98:99]
	v_pk_add_f32 v[116:117], v[92:93], v[96:97]
	v_pk_add_f32 v[118:119], v[102:103], v[106:107]
	v_pk_add_f32 v[120:121], v[100:101], v[104:105]
	v_pk_add_f32 v[114:115], v[114:115], v[118:119]
	v_pk_add_f32 v[116:117], v[116:117], v[120:121]
	v_add_f32_e32 v116, v117, v116
	v_add_f32_e32 v114, v114, v115
	v_add_f32_e32 v114, v116, v114
	v_fmamk_f32 v114, v114, 0x3a800000, v111
	v_rsq_f32_e32 v114, v114
	ds_write_b32 v112, v114 offset:10240

.LBB0_1646:
	s_ashr_i32 s23, s22, 31
	s_lshl_b64 s[26:27], s[22:23], 19
	s_add_u32 s26, s14, s26
	s_addc_u32 s27, s15, s27
	s_and_b64 s[28:29], s[4:5], exec
	s_cselect_b32 s23, s27, s37
	s_cselect_b32 s58, s26, s36
	s_ashr_i32 s11, s10, 31
	s_lshl_b64 s[28:29], s[10:11], 19
	s_add_u32 s28, s45, s28
	s_addc_u32 s29, s46, s29
	s_and_b64 s[34:35], s[4:5], exec
	s_cselect_b32 s11, s29, s39
	s_cselect_b32 s59, s28, s38
	s_add_u32 s36, s36, 0x40080
	s_addc_u32 s37, s37, 0
	s_add_u32 s60, s38, 0x100
	s_addc_u32 s61, s39, 0
	s_mov_b32 s62, -2
	s_setprio 0
	s_cmp_lg_u32 s56, 1
	s_cselect_b32 s100, s99, 0
	s_cmp_lg_u32 s100, 0
	s_cbranch_scc0 .Lmy_nobar2_17
	s_barrier

.LBB0_1708:
	s_setprio 0
	s_cmp_lt_i32 s74, 19
	s_cselect_b64 s[0:1], -1, 0
	s_cmp_gt_i32 s75, 18
	s_cselect_b64 s[4:5], -1, 0
	s_and_b64 s[0:1], s[0:1], s[4:5]
	s_andn2_b64 vcc, exec, s[0:1]
	s_cbranch_vccnz .LBB0_1809
	s_cmpk_lt_i32 s2, 0x200
	s_cselect_b64 s[0:1], -1, 0
	s_cmpk_gt_i32 s2, 0x1ff
	v_readfirstlane_b32 s6, v128
	s_cbranch_scc0 .LBB0_1712
	s_andn2_b64 vcc, exec, s[0:1]
	s_cbranch_vccz .LBB0_1717

.LBB0_1732:
	s_add_u32 s30, s30, 0xb0080
	s_addc_u32 s31, s31, 0
	s_add_u32 s13, s36, 0x100
	s_addc_u32 s57, s37, 0
	s_mov_b32 s58, -2
	s_waitcnt lgkmcnt(0)
	s_setprio 0
	s_cmp_lg_u32 s54, 1
	s_cselect_b32 s100, s99, 0
	s_cmp_lg_u32 s100, 0
	s_cbranch_scc0 .Lmy_nobar2_18
	s_barrier

.LBB0_1809:
	s_setprio 0
	s_cmp_lt_i32 s74, 20
	s_cselect_b64 s[0:1], -1, 0
	s_cmp_gt_i32 s75, 19
	s_cselect_b64 s[4:5], -1, 0
	s_and_b64 s[0:1], s[0:1], s[4:5]
	s_andn2_b64 vcc, exec, s[0:1]
	s_cbranch_vccnz .LBB0_1918
	s_waitcnt vmcnt(0)
	v_lshlrev_b32_e32 v8, 2, v128
	s_ashr_i32 s3, s2, 31
	v_add_u32_e32 v0, 0, v8
	s_ashr_i32 s48, s72, 31
	s_mov_b32 s49, s72
	v_and_b32_e32 v4, 0xff, v128
	v_add_u32_e32 v5, 0xfffffe00, v128
	v_add_u32_e32 v6, 0x20000, v0
	v_lshrrev_b32_e32 v7, 8, v128
	s_mov_b64 s[0:1], 0
	s_waitcnt lgkmcnt(0)
	v_mov_b64_e32 v[0:1], s[2:3]
	s_mov_b64 s[4:5], 0x600
	s_mov_b32 s10, 0x2aaaaaab
	s_movk_i32 s11, 0x60
	v_mov_b32_e32 v9, 0x358637bd
	s_movk_i32 s12, 0x8ff
	v_mov_b32_e32 v10, 0xc0
	v_mov_b32_e32 v11, 0xc1
	v_and_b32_e32 v110, 0xff, v128
	s_lshr_b32 s98, s91, 2
	v_mov_b32_e32 v111, 0x358637bd
	s_mul_i32 s99, s98, s72
	s_add_i32 s99, s99, s2
	s_cmp_lt_u32 s99, 0x600
	s_cselect_b32 s99, s99, s2
	s_and_b32 s100, s99, 7
	s_mul_i32 s100, s100, 0xc0
	s_lshr_b32 s101, s99, 3
	s_add_i32 s100, s100, s101
	s_mul_hi_u32 s101, s100, 0x2aaaaab
	s_lshl_b32 s101, s101, 3
	s_and_b32 s100, s100, 7
	s_or_b32 s101, s101, s100
	s_lshl_b32 s101, s101, 8
	v_add_u32_e32 v108, s101, v110
	v_lshlrev_b32_e32 v108, 6, v108
	v_mov_b32_e32 v109, 0
	v_lshl_add_u64 v[108:109], s[18:19], 0, v[108:109]
	global_load_dwordx4 v[12:15], v[108:109], off
	global_load_dwordx4 v[16:19], v[108:109], off offset:16
	global_load_dwordx4 v[20:23], v[108:109], off offset:32
	global_load_dwordx4 v[24:27], v[108:109], off offset:48
	s_add_i32 s98, s98, 2
	s_mul_i32 s99, s98, s72
	s_add_i32 s99, s99, s2
	s_cmp_lt_u32 s99, 0x600
	s_cselect_b32 s99, s99, s2
	s_and_b32 s100, s99, 7
	s_mul_i32 s100, s100, 0xc0
	s_lshr_b32 s101, s99, 3
	s_add_i32 s100, s100, s101
	s_mul_hi_u32 s101, s100, 0x2aaaaab
	s_lshl_b32 s101, s101, 3
	s_and_b32 s100, s100, 7
	s_or_b32 s101, s101, s100
	s_lshl_b32 s101, s101, 8
	v_add_u32_e32 v108, s101, v110
	v_lshlrev_b32_e32 v108, 6, v108
	v_mov_b32_e32 v109, 0
	v_lshl_add_u64 v[108:109], s[18:19], 0, v[108:109]
	global_load_dwordx4 v[28:31], v[108:109], off
	global_load_dwordx4 v[32:35], v[108:109], off offset:16
	global_load_dwordx4 v[36:39], v[108:109], off offset:32
	global_load_dwordx4 v[40:43], v[108:109], off offset:48
	s_add_i32 s98, s98, 2
	s_mul_i32 s99, s98, s72
	s_add_i32 s99, s99, s2
	s_cmp_lt_u32 s99, 0x600
	s_cselect_b32 s99, s99, s2
	s_and_b32 s100, s99, 7
	s_mul_i32 s100, s100, 0xc0
	s_lshr_b32 s101, s99, 3
	s_add_i32 s100, s100, s101
	s_mul_hi_u32 s101, s100, 0x2aaaaab
	s_lshl_b32 s101, s101, 3
	s_and_b32 s100, s100, 7
	s_or_b32 s101, s101, s100
	s_lshl_b32 s101, s101, 8
	v_add_u32_e32 v108, s101, v110
	v_lshlrev_b32_e32 v108, 6, v108
	v_mov_b32_e32 v109, 0
	v_lshl_add_u64 v[108:109], s[18:19], 0, v[108:109]
	global_load_dwordx4 v[44:47], v[108:109], off
	global_load_dwordx4 v[48:51], v[108:109], off offset:16
	global_load_dwordx4 v[52:55], v[108:109], off offset:32
	global_load_dwordx4 v[56:59], v[108:109], off offset:48
	s_add_i32 s98, s98, 2
	v_lshlrev_b32_e32 v112, 2, v128
	v_add_u32_e32 v112, 0x20000, v112
	s_waitcnt vmcnt(8)
	v_pk_add_f32 v[114:115], v[14:15], v[18:19]
	v_pk_add_f32 v[116:117], v[12:13], v[16:17]
	v_pk_add_f32 v[118:119], v[22:23], v[26:27]
	v_pk_add_f32 v[120:121], v[20:21], v[24:25]
	v_pk_add_f32 v[114:115], v[114:115], v[118:119]
	v_pk_add_f32 v[116:117], v[116:117], v[120:121]
	v_add_f32_e32 v116, v117, v116
	v_add_f32_e32 v114, v114, v115
	v_add_f32_e32 v114, v116, v114
	v_fmamk_f32 v114, v114, 0x3a800000, v111
	v_rsq_f32_e32 v114, v114
	ds_write_b32 v112, v114
	s_waitcnt vmcnt(4)
	v_pk_add_f32 v[114:115], v[30:31], v[34:35]
	v_pk_add_f32 v[116:117], v[28:29], v[32:33]
	v_pk_add_f32 v[118:119], v[38:39], v[42:43]
	v_pk_add_f32 v[120:121], v[36:37], v[40:41]
	v_pk_add_f32 v[114:115], v[114:115], v[118:119]
	v_pk_add_f32 v[116:117], v[116:117], v[120:121]
	v_add_f32_e32 v116, v117, v116
	v_add_f32_e32 v114, v114, v115
	v_add_f32_e32 v114, v116, v114
	v_fmamk_f32 v114, v114, 0x3a800000, v111
	v_rsq_f32_e32 v114, v114
	ds_write_b32 v112, v114 offset:2048
	s_waitcnt vmcnt(0)
	v_pk_add_f32 v[114:115], v[46:47], v[50:51]
	v_pk_add_f32 v[116:117], v[44:45], v[48:49]
	v_pk_add_f32 v[118:119], v[54:55], v[58:59]
	v_pk_add_f32 v[120:121], v[52:53], v[56:57]
	v_pk_add_f32 v[114:115], v[114:115], v[118:119]
	v_pk_add_f32 v[116:117], v[116:117], v[120:121]
	v_add_f32_e32 v116, v117, v116
	v_add_f32_e32 v114, v114, v115
	v_add_f32_e32 v114, v116, v114
	v_fmamk_f32 v114, v114, 0x3a800000, v111
	v_rsq_f32_e32 v114, v114
	ds_write_b32 v112, v114 offset:4096

.LBB0_1825:
	s_ashr_i32 s37, s36, 31
	s_lshl_b64 s[12:13], s[36:37], 19
	s_add_u32 s38, s14, s12
	s_addc_u32 s39, s15, s13
	s_and_b64 s[12:13], s[4:5], exec
	s_cselect_b32 s7, s39, s43
	s_cselect_b32 s8, s38, s42
	s_ashr_i32 s31, s30, 31
	s_lshl_b64 s[12:13], s[30:31], 19
	s_add_u32 s40, s51, s12
	s_addc_u32 s41, s52, s13
	s_and_b64 s[12:13], s[4:5], exec
	s_cselect_b32 s12, s41, s45
	s_cselect_b32 s13, s40, s44
	s_add_u32 s42, s42, 0x40080
	s_addc_u32 s43, s43, 0
	s_add_u32 s31, s44, 0x100
	s_addc_u32 s37, s45, 0
	s_mov_b32 s65, -2
	s_waitcnt lgkmcnt(0)
	s_setprio 0
	s_cmp_lg_u32 s63, 1
	s_cselect_b32 s100, s99, 0
	s_cmp_lg_u32 s100, 0
	s_cbranch_scc0 .Lmy_nobar2_19
	s_barrier

.LBB0_1918:
	s_setprio 0
	s_cmp_lt_i32 s74, 21
	s_cselect_b64 s[0:1], -1, 0
	s_cmp_gt_i32 s75, 20
	s_cselect_b64 s[4:5], -1, 0
	s_and_b64 s[0:1], s[0:1], s[4:5]
	s_andn2_b64 vcc, exec, s[0:1]
	s_cbranch_vccnz .LBB0_1980
	s_mov_b32 s0, 0x400000
	v_cmp_gt_i32_e32 vcc, s0, v156
	s_and_saveexec_b64 s[0:1], vcc
	s_cbranch_execz .LBB0_1926
	s_add_u32 s4, s70, 0x13700000
	s_addc_u32 s5, s71, 0
	s_add_u32 s6, s24, 0x3000
	s_addc_u32 s7, s25, 0
	s_lshl_b32 s3, s72, 9
	s_add_u32 s8, s24, 0x4000
	s_addc_u32 s9, s25, 0
	v_readlane_b32 s12, v238, 0
	s_add_u32 s10, s24, 0x5000
	s_waitcnt vmcnt(0)
	v_lshlrev_b32_e32 v0, 3, v128
	v_readlane_b32 s13, v238, 1
	s_addc_u32 s11, s25, 0
	v_lshl_add_u32 v20, s12, 12, v0
	s_lshl_b32 s12, s72, 12
	s_mov_b64 s[22:23], 0
	s_movk_i32 s13, 0x7ff
	s_mov_b32 s26, 0x3fffff
	s_branch .LBB0_1922

.LBB0_1980:
	s_setprio 0
	s_cmp_lt_i32 s74, 22
	s_cselect_b64 s[0:1], -1, 0
	s_cmp_gt_i32 s75, 21
	s_cselect_b64 s[4:5], -1, 0
	s_and_b64 s[0:1], s[0:1], s[4:5]
	s_andn2_b64 vcc, exec, s[0:1]
	s_cbranch_vccnz .LBB0_2077
	s_cmpk_lt_i32 s2, 0x200
	s_cselect_b64 s[4:5], -1, 0
	s_cmpk_gt_i32 s2, 0x1ff
	v_readfirstlane_b32 s6, v128
	s_cbranch_scc0 .LBB0_1984
	s_andn2_b64 vcc, exec, s[4:5]
	s_cbranch_vccz .LBB0_1989

.LBB0_2000:
	s_ashr_i32 s27, s26, 31
	s_lshl_b64 s[12:13], s[26:27], 19
	s_add_u32 s28, s20, s12
	s_addc_u32 s29, s21, s13
	s_and_b64 s[12:13], s[6:7], exec
	s_cselect_b32 s12, s29, s39
	s_cselect_b32 s13, s28, s38
	s_ashr_i32 s25, s24, 31
	s_lshl_b64 s[30:31], s[24:25], 19
	s_add_u32 s30, s3, s30
	s_addc_u32 s31, s44, s31
	s_and_b64 s[34:35], s[6:7], exec
	s_cselect_b32 s25, s31, s41
	s_cselect_b32 s27, s30, s40
	s_add_u32 s38, s38, 0x40080
	s_addc_u32 s39, s39, 0
	s_add_u32 s37, s40, 0x100
	s_addc_u32 s59, s41, 0
	s_mov_b32 s60, -2
	s_waitcnt lgkmcnt(0)
	s_setprio 0
	s_cmp_lg_u32 s58, 1
	s_cselect_b32 s100, s99, 0
	s_cmp_lg_u32 s100, 0
	s_cbranch_scc0 .Lmy_nobar2_21
	s_barrier

.LBB0_2077:
	s_setprio 0
	s_cmp_lt_i32 s74, 23
	s_cselect_b64 s[0:1], -1, 0
	s_cmp_gt_i32 s75, 22
	s_cselect_b64 s[4:5], -1, 0
	s_and_b64 s[0:1], s[0:1], s[4:5]
	s_andn2_b64 vcc, exec, s[0:1]
	s_cbranch_vccnz .LBB0_2152
	s_waitcnt vmcnt(0)
	v_lshlrev_b32_e32 v8, 2, v128
	s_ashr_i32 s3, s2, 31
	v_add_u32_e32 v0, 0, v8
	s_ashr_i32 s36, s72, 31
	s_mov_b32 s37, s72
	v_and_b32_e32 v4, 0xff, v128
	v_add_u32_e32 v5, 0xfffffe00, v128
	v_add_u32_e32 v6, 0x20000, v0
	s_mov_b64 s[0:1], 0
	s_waitcnt lgkmcnt(0)
	v_mov_b64_e32 v[0:1], s[2:3]
	s_mov_b64 s[4:5], 0xb00
	s_mov_b32 s10, 0x2e8ba2e9
	s_movk_i32 s11, 0xb0
	v_mov_b32_e32 v7, 0x358637bd
	s_movk_i32 s12, 0x8ff
	v_mov_b32_e32 v9, 0x160
	v_mov_b32_e32 v10, 0x161
	v_and_b32_e32 v110, 0xff, v128
	s_lshr_b32 s98, s91, 2
	v_mov_b32_e32 v111, 0x358637bd
	s_mul_i32 s99, s98, s72
	s_add_i32 s99, s99, s2
	s_cmp_lt_u32 s99, 0xb00
	s_cselect_b32 s99, s99, s2
	s_and_b32 s100, s99, 7
	s_mul_i32 s100, s100, 0x160
	s_lshr_b32 s101, s99, 3
	s_add_i32 s100, s100, s101
	s_mul_hi_u32 s101, s100, 0x1745d18
	s_lshl_b32 s101, s101, 3
	s_and_b32 s100, s100, 7
	s_or_b32 s101, s101, s100
	s_lshl_b32 s101, s101, 8
	v_add_u32_e32 v108, s101, v110
	v_lshlrev_b32_e32 v108, 6, v108
	v_mov_b32_e32 v109, 0
	v_lshl_add_u64 v[108:109], s[18:19], 0, v[108:109]
	global_load_dwordx4 v[12:15], v[108:109], off
	global_load_dwordx4 v[16:19], v[108:109], off offset:16
	global_load_dwordx4 v[20:23], v[108:109], off offset:32
	global_load_dwordx4 v[24:27], v[108:109], off offset:48
	s_add_i32 s98, s98, 2
	s_mul_i32 s99, s98, s72
	s_add_i32 s99, s99, s2
	s_cmp_lt_u32 s99, 0xb00
	s_cselect_b32 s99, s99, s2
	s_and_b32 s100, s99, 7
	s_mul_i32 s100, s100, 0x160
	s_lshr_b32 s101, s99, 3
	s_add_i32 s100, s100, s101
	s_mul_hi_u32 s101, s100, 0x1745d18
	s_lshl_b32 s101, s101, 3
	s_and_b32 s100, s100, 7
	s_or_b32 s101, s101, s100
	s_lshl_b32 s101, s101, 8
	v_add_u32_e32 v108, s101, v110
	v_lshlrev_b32_e32 v108, 6, v108
	v_mov_b32_e32 v109, 0
	v_lshl_add_u64 v[108:109], s[18:19], 0, v[108:109]
	global_load_dwordx4 v[28:31], v[108:109], off
	global_load_dwordx4 v[32:35], v[108:109], off offset:16
	global_load_dwordx4 v[36:39], v[108:109], off offset:32
	global_load_dwordx4 v[40:43], v[108:109], off offset:48
	s_add_i32 s98, s98, 2
	s_mul_i32 s99, s98, s72
	s_add_i32 s99, s99, s2
	s_cmp_lt_u32 s99, 0xb00
	s_cselect_b32 s99, s99, s2
	s_and_b32 s100, s99, 7
	s_mul_i32 s100, s100, 0x160
	s_lshr_b32 s101, s99, 3
	s_add_i32 s100, s100, s101
	s_mul_hi_u32 s101, s100, 0x1745d18
	s_lshl_b32 s101, s101, 3
	s_and_b32 s100, s100, 7
	s_or_b32 s101, s101, s100
	s_lshl_b32 s101, s101, 8
	v_add_u32_e32 v108, s101, v110
	v_lshlrev_b32_e32 v108, 6, v108
	v_mov_b32_e32 v109, 0
	v_lshl_add_u64 v[108:109], s[18:19], 0, v[108:109]
	global_load_dwordx4 v[44:47], v[108:109], off
	global_load_dwordx4 v[48:51], v[108:109], off offset:16
	global_load_dwordx4 v[52:55], v[108:109], off offset:32
	global_load_dwordx4 v[56:59], v[108:109], off offset:48
	s_add_i32 s98, s98, 2
	s_mul_i32 s99, s98, s72
	s_add_i32 s99, s99, s2
	s_cmp_lt_u32 s99, 0xb00
	s_cselect_b32 s99, s99, s2
	s_and_b32 s100, s99, 7
	s_mul_i32 s100, s100, 0x160
	s_lshr_b32 s101, s99, 3
	s_add_i32 s100, s100, s101
	s_mul_hi_u32 s101, s100, 0x1745d18
	s_lshl_b32 s101, s101, 3
	s_and_b32 s100, s100, 7
	s_or_b32 s101, s101, s100
	s_lshl_b32 s101, s101, 8
	v_add_u32_e32 v108, s101, v110
	v_lshlrev_b32_e32 v108, 6, v108
	v_mov_b32_e32 v109, 0
	v_lshl_add_u64 v[108:109], s[18:19], 0, v[108:109]
	global_load_dwordx4 v[60:63], v[108:109], off
	global_load_dwordx4 v[64:67], v[108:109], off offset:16
	global_load_dwordx4 v[68:71], v[108:109], off offset:32
	global_load_dwordx4 v[72:75], v[108:109], off offset:48
	s_add_i32 s98, s98, 2
	s_mul_i32 s99, s98, s72
	s_add_i32 s99, s99, s2
	s_cmp_lt_u32 s99, 0xb00
	s_cselect_b32 s99, s99, s2
	s_and_b32 s100, s99, 7
	s_mul_i32 s100, s100, 0x160
	s_lshr_b32 s101, s99, 3
	s_add_i32 s100, s100, s101
	s_mul_hi_u32 s101, s100, 0x1745d18
	s_lshl_b32 s101, s101, 3
	s_and_b32 s100, s100, 7
	s_or_b32 s101, s101, s100
	s_lshl_b32 s101, s101, 8
	v_add_u32_e32 v108, s101, v110
	v_lshlrev_b32_e32 v108, 6, v108
	v_mov_b32_e32 v109, 0
	v_lshl_add_u64 v[108:109], s[18:19], 0, v[108:109]
	global_load_dwordx4 v[76:79], v[108:109], off
	global_load_dwordx4 v[80:83], v[108:109], off offset:16
	global_load_dwordx4 v[84:87], v[108:109], off offset:32
	global_load_dwordx4 v[88:91], v[108:109], off offset:48
	s_add_i32 s98, s98, 2
	s_mul_i32 s99, s98, s72
	s_add_i32 s99, s99, s2
	s_cmp_lt_u32 s99, 0xb00
	s_cselect_b32 s99, s99, s2
	s_and_b32 s100, s99, 7
	s_mul_i32 s100, s100, 0x160
	s_lshr_b32 s101, s99, 3
	s_add_i32 s100, s100, s101
	s_mul_hi_u32 s101, s100, 0x1745d18
	s_lshl_b32 s101, s101, 3
	s_and_b32 s100, s100, 7
	s_or_b32 s101, s101, s100
	s_lshl_b32 s101, s101, 8
	v_add_u32_e32 v108, s101, v110
	v_lshlrev_b32_e32 v108, 6, v108
	v_mov_b32_e32 v109, 0
	v_lshl_add_u64 v[108:109], s[18:19], 0, v[108:109]
	global_load_dwordx4 v[92:95], v[108:109], off
	global_load_dwordx4 v[96:99], v[108:109], off offset:16
	global_load_dwordx4 v[100:103], v[108:109], off offset:32
	global_load_dwordx4 v[104:107], v[108:109], off offset:48
	s_add_i32 s98, s98, 2
	v_lshlrev_b32_e32 v112, 2, v128
	v_add_u32_e32 v112, 0x20000, v112
	s_waitcnt vmcnt(20)
	v_pk_add_f32 v[114:115], v[14:15], v[18:19]
	v_pk_add_f32 v[116:117], v[12:13], v[16:17]
	v_pk_add_f32 v[118:119], v[22:23], v[26:27]
	v_pk_add_f32 v[120:121], v[20:21], v[24:25]
	v_pk_add_f32 v[114:115], v[114:115], v[118:119]
	v_pk_add_f32 v[116:117], v[116:117], v[120:121]
	v_add_f32_e32 v116, v117, v116
	v_add_f32_e32 v114, v114, v115
	v_add_f32_e32 v114, v116, v114
	v_fmamk_f32 v114, v114, 0x3a800000, v111
	v_rsq_f32_e32 v114, v114
	ds_write_b32 v112, v114
	s_waitcnt vmcnt(16)
	v_pk_add_f32 v[114:115], v[30:31], v[34:35]
	v_pk_add_f32 v[116:117], v[28:29], v[32:33]
	v_pk_add_f32 v[118:119], v[38:39], v[42:43]
	v_pk_add_f32 v[120:121], v[36:37], v[40:41]
	v_pk_add_f32 v[114:115], v[114:115], v[118:119]
	v_pk_add_f32 v[116:117], v[116:117], v[120:121]
	v_add_f32_e32 v116, v117, v116
	v_add_f32_e32 v114, v114, v115
	v_add_f32_e32 v114, v116, v114
	v_fmamk_f32 v114, v114, 0x3a800000, v111
	v_rsq_f32_e32 v114, v114
	ds_write_b32 v112, v114 offset:2048
	s_waitcnt vmcnt(12)
	v_pk_add_f32 v[114:115], v[46:47], v[50:51]
	v_pk_add_f32 v[116:117], v[44:45], v[48:49]
	v_pk_add_f32 v[118:119], v[54:55], v[58:59]
	v_pk_add_f32 v[120:121], v[52:53], v[56:57]
	v_pk_add_f32 v[114:115], v[114:115], v[118:119]
	v_pk_add_f32 v[116:117], v[116:117], v[120:121]
	v_add_f32_e32 v116, v117, v116
	v_add_f32_e32 v114, v114, v115
	v_add_f32_e32 v114, v116, v114
	v_fmamk_f32 v114, v114, 0x3a800000, v111
	v_rsq_f32_e32 v114, v114
	ds_write_b32 v112, v114 offset:4096
	s_waitcnt vmcnt(8)
	v_pk_add_f32 v[114:115], v[62:63], v[66:67]
	v_pk_add_f32 v[116:117], v[60:61], v[64:65]
	v_pk_add_f32 v[118:119], v[70:71], v[74:75]
	v_pk_add_f32 v[120:121], v[68:69], v[72:73]
	v_pk_add_f32 v[114:115], v[114:115], v[118:119]
	v_pk_add_f32 v[116:117], v[116:117], v[120:121]
	v_add_f32_e32 v116, v117, v116
	v_add_f32_e32 v114, v114, v115
	v_add_f32_e32 v114, v116, v114
	v_fmamk_f32 v114, v114, 0x3a800000, v111
	v_rsq_f32_e32 v114, v114
	ds_write_b32 v112, v114 offset:6144
	s_waitcnt vmcnt(4)
	v_pk_add_f32 v[114:115], v[78:79], v[82:83]
	v_pk_add_f32 v[116:117], v[76:77], v[80:81]
	v_pk_add_f32 v[118:119], v[86:87], v[90:91]
	v_pk_add_f32 v[120:121], v[84:85], v[88:89]
	v_pk_add_f32 v[114:115], v[114:115], v[118:119]
	v_pk_add_f32 v[116:117], v[116:117], v[120:121]
	v_add_f32_e32 v116, v117, v116
	v_add_f32_e32 v114, v114, v115
	v_add_f32_e32 v114, v116, v114
	v_fmamk_f32 v114, v114, 0x3a800000, v111
	v_rsq_f32_e32 v114, v114
	ds_write_b32 v112, v114 offset:8192
	s_waitcnt vmcnt(0)
	v_pk_add_f32 v[114:115], v[94:95], v[98:99]
	v_pk_add_f32 v[116:117], v[92:93], v[96:97]
	v_pk_add_f32 v[118:119], v[102:103], v[106:107]
	v_pk_add_f32 v[120:121], v[100:101], v[104:105]
	v_pk_add_f32 v[114:115], v[114:115], v[118:119]
	v_pk_add_f32 v[116:117], v[116:117], v[120:121]
	v_add_f32_e32 v116, v117, v116
	v_add_f32_e32 v114, v114, v115
	v_add_f32_e32 v114, v116, v114
	v_fmamk_f32 v114, v114, 0x3a800000, v111
	v_rsq_f32_e32 v114, v114
	ds_write_b32 v112, v114 offset:10240

.LBB0_2090:
	s_ashr_i32 s19, s18, 31
	s_lshl_b64 s[20:21], s[18:19], 19
	s_add_u32 s20, s14, s20
	s_addc_u32 s21, s15, s21
	s_and_b64 s[22:23], s[4:5], exec
	s_cselect_b32 s19, s21, s27
	s_cselect_b32 s52, s20, s26
	s_ashr_i32 s11, s10, 31
	s_lshl_b64 s[22:23], s[10:11], 19
	s_add_u32 s22, s39, s22
	s_addc_u32 s23, s40, s23
	s_and_b64 s[30:31], s[4:5], exec
	s_cselect_b32 s11, s23, s29
	s_cselect_b32 s53, s22, s28
	s_add_u32 s26, s26, 0x40080
	s_addc_u32 s27, s27, 0
	s_add_u32 s54, s28, 0x100
	s_addc_u32 s55, s29, 0
	s_mov_b32 s56, -2
	s_setprio 0
	s_cmp_lg_u32 s50, 1
	s_cselect_b32 s100, s99, 0
	s_cmp_lg_u32 s100, 0
	s_cbranch_scc0 .Lmy_nobar2_22
	s_barrier

.LBB0_2152:
	s_setprio 0
	s_cmp_lt_i32 s74, 24
	s_cselect_b64 s[0:1], -1, 0
	s_cmp_gt_i32 s75, 23
	s_cselect_b64 s[4:5], -1, 0
	s_and_b64 s[0:1], s[0:1], s[4:5]
	s_andn2_b64 vcc, exec, s[0:1]
	s_cbranch_vccnz .LBB0_2235
	s_cmpk_gt_i32 s2, 0x1ff
	v_readfirstlane_b32 s4, v128
	s_cbranch_scc1 .LBB0_2181
	s_ashr_i32 s3, s2, 31
	s_lshr_b32 s0, s3, 29
	s_add_i32 s7, s2, s0
	s_and_b32 s0, s7, -8
	s_sub_i32 s5, s2, s0
	s_cmp_gt_i32 s5, -1
	s_cbranch_scc0 .LBB0_2156
	s_lshl_b32 s6, s5, 6
	s_ashr_i32 s1, s7, 3
	s_cbranch_execz .LBB0_2157
	s_branch .LBB0_2158

.LBB0_2173:
	s_add_u32 s28, s28, 0xb0080
	s_addc_u32 s29, s29, 0
	s_add_u32 s54, s30, 0x100
	s_addc_u32 s55, s31, 0
	s_mov_b32 s56, -2
	s_setprio 0
	s_cmp_lg_u32 s45, 1
	s_cselect_b32 s100, s99, 0
	s_cmp_lg_u32 s100, 0
	s_cbranch_scc0 .Lmy_nobar2_23
	s_barrier
